# RG-LRU scan loop rewritten by hand: MFMA interval / VALU interval per step, backward waves one barrier behind forward waves (same arithmetic)
# speedup vs baseline: 1.0274x; 1.0158x over previous
.LBB0_598:
	s_lshl_b32 s4, s84, 5
	s_and_b32 s68, s4, 32
	s_bfe_u32 s70, s84, 0x40001
	s_or_b32 s34, s68, s3
	s_lshl_b32 s67, s70, 6
	v_or_b32_e32 v164, s34, v3
	v_or_b32_e32 v4, s67, v164
	v_lshlrev_b32_e32 v128, 2, v4
	v_lshl_add_u64 v[134:135], s[90:91], 0, v[128:129]
	v_add_co_u32_e32 v4, vcc, s53, v134
	s_ashr_i32 s69, s84, 5
	s_nop 0
	v_addc_co_u32_e32 v5, vcc, 0, v135, vcc
	v_add_co_u32_e32 v6, vcc, s55, v134
	s_lshl_b32 s4, s69, 4
	s_nop 0
	v_addc_co_u32_e32 v7, vcc, 0, v135, vcc
	global_load_dword v8, v[4:5], off offset:576
	global_load_dword v9, v[6:7], off offset:576
	v_add_co_u32_e32 v4, vcc, s56, v134
	s_or_b32 s4, s4, s70
	s_nop 0
	v_addc_co_u32_e32 v5, vcc, 0, v135, vcc
	v_add_co_u32_e32 v6, vcc, s57, v134
	s_mul_i32 s28, s4, 0x804
	s_nop 0
	v_addc_co_u32_e32 v7, vcc, 0, v135, vcc
	global_load_dword v10, v[4:5], off offset:576
	s_nop 0
	global_load_dword v6, v[6:7], off offset:576
	v_add_co_u32_e32 v4, vcc, 0xd000, v134
	s_ashr_i32 s29, s28, 31
	s_nop 0
	v_addc_co_u32_e32 v5, vcc, 0, v135, vcc
	global_load_dword v133, v[4:5], off offset:576
	s_lshl_b64 s[28:29], s[28:29], 7
	s_add_u32 s50, s42, s28
	s_addc_u32 s51, s43, s29
	s_bitcmp1_b32 s84, 0
	s_cselect_b64 s[28:29], -1, 0
	s_mov_b64 s[26:27], -1
	s_lshl_b32 s71, s70, 10
	s_and_b64 vcc, exec, s[28:29]
	s_waitcnt vmcnt(4)
	v_bfe_u32 v4, v8, 16, 1
	v_add3_u32 v184, v8, v4, s54
	s_waitcnt vmcnt(3)
	v_bfe_u32 v5, v9, 16, 1
	v_add3_u32 v185, v9, v5, s54
	s_waitcnt vmcnt(2)
	v_bfe_u32 v4, v10, 16, 1
	v_add3_u32 v195, v10, v4, s54
	s_waitcnt vmcnt(1)
	v_bfe_u32 v4, v6, 16, 1
	v_add3_u32 v197, v6, v4, s54
	s_waitcnt vmcnt(0)
	s_cmpk_gt_u32 s85, 0xff
	s_cbranch_scc1 .Lrec2_bwd
	v_and_b32_e32 v252, 15, v157
	v_lshrrev_b32_e32 v253, 4, v157
	s_bfe_u32 s5, s85, 0x10006
	s_bfe_u32 s6, s85, 0x10007
	s_and_b32 s8, s84, 1
	v_readlane_b32 s26, v254, 13
	v_readlane_b32 s27, v254, 14
	s_nop 3
	s_lshl_b32 s9, s70, 2
	s_lshl_b32 s52, s9, 15
	s_add_u32 s26, s26, 0x100000
	s_addc_u32 s27, s27, 0
	s_add_u32 s26, s26, s52
	s_addc_u32 s27, s27, 0
	v_add_u32_e32 v8, s34, v252
	v_lshlrev_b32_e32 v9, 7, v8
	v_lshl_add_u32 v9, v253, 4, v9
	s_lshl_b32 s64, s8, 6
	s_xor_b32 s71, s64, 64
	v_add_u32_e32 v10, s64, v9
	v_add_u32_e32 v255, s71, v9
	s_add_u32 s38, s26, 0x0
	s_addc_u32 s39, s27, 0
	global_load_dwordx4 v[20:23], v10, s[38:39]
	global_load_dwordx4 v[24:27], v255, s[38:39]
	s_add_u32 s38, s26, 0x2000
	s_addc_u32 s39, s27, 0
	global_load_dwordx4 v[28:31], v10, s[38:39]
	global_load_dwordx4 v[32:35], v255, s[38:39]
	s_add_u32 s38, s26, 0x4000
	s_addc_u32 s39, s27, 0
	global_load_dwordx4 v[36:39], v10, s[38:39]
	global_load_dwordx4 v[40:43], v255, s[38:39]
	s_add_u32 s38, s26, 0x6000
	s_addc_u32 s39, s27, 0
	global_load_dwordx4 v[44:47], v10, s[38:39]
	global_load_dwordx4 v[48:51], v255, s[38:39]
	s_add_u32 s38, s26, 0x8000
	s_addc_u32 s39, s27, 0
	global_load_dwordx4 v[52:55], v10, s[38:39]
	global_load_dwordx4 v[56:59], v255, s[38:39]
	s_add_u32 s38, s26, 0xa000
	s_addc_u32 s39, s27, 0
	global_load_dwordx4 v[60:63], v10, s[38:39]
	global_load_dwordx4 v[64:67], v255, s[38:39]
	s_add_u32 s38, s26, 0xc000
	s_addc_u32 s39, s27, 0
	global_load_dwordx4 v[68:71], v10, s[38:39]
	global_load_dwordx4 v[72:75], v255, s[38:39]
	s_add_u32 s38, s26, 0xe000
	s_addc_u32 s39, s27, 0
	global_load_dwordx4 v[76:79], v10, s[38:39]
	global_load_dwordx4 v[80:83], v255, s[38:39]
	s_lshl_b32 s52, s9, 8
	s_add_i32 s52, s52, 0x15240
	v_lshlrev_b32_e32 v8, 2, v8
	v_add_u32_e32 v9, s52, v8
	global_load_dword v128, v9, s[90:91]
	global_load_dword v178, v9, s[90:91] offset:256
	s_lshl_b32 s52, s70, 8
	s_add_i32 s52, s52, 0x12240
	v_add_u32_e32 v9, s52, v8
	global_load_dword v179, v9, s[90:91]
	v_lshlrev_b32_e32 v198, 3, v253
	v_sub_u32_e32 v198, v252, v198
	v_lshl_add_u32 v198, s6, 4, v198
	v_cmp_gt_u32_e32 vcc, 8, v198
	v_and_b32_e32 v199, 1, v198
	v_lshlrev_b32_e32 v199, 4, v199
	v_lshrrev_b32_e32 v200, 1, v198
	s_nop 1
	v_cndmask_b32_e32 v200, 7, v200, vcc
	v_cmp_eq_u32_e64 s[58:59], 0, v200
	v_cmp_eq_u32_e64 s[60:61], 1, v200
	v_cmp_eq_u32_e64 s[98:99], 2, v200
	v_cmp_eq_u32_e64 s[100:101], 3, v200
	s_nop 1
	v_lshrrev_b32_e32 v201, 16, v184
	v_lshlrev_b32_e32 v201, v199, v201
	v_cndmask_b32_e64 v84, 0, v201, s[58:59]
	v_cndmask_b32_e64 v85, 0, v201, s[60:61]
	v_cndmask_b32_e64 v86, 0, v201, s[98:99]
	v_cndmask_b32_e64 v87, 0, v201, s[100:101]
	v_lshrrev_b32_e32 v201, 16, v185
	v_lshlrev_b32_e32 v201, v199, v201
	v_cndmask_b32_e64 v88, 0, v201, s[58:59]
	v_cndmask_b32_e64 v89, 0, v201, s[60:61]
	v_cndmask_b32_e64 v90, 0, v201, s[98:99]
	v_cndmask_b32_e64 v91, 0, v201, s[100:101]
	v_lshrrev_b32_e32 v201, 16, v195
	v_lshlrev_b32_e32 v201, v199, v201
	v_cndmask_b32_e64 v92, 0, v201, s[58:59]
	v_cndmask_b32_e64 v93, 0, v201, s[60:61]
	v_cndmask_b32_e64 v94, 0, v201, s[98:99]
	v_cndmask_b32_e64 v95, 0, v201, s[100:101]
	v_lshrrev_b32_e32 v201, 16, v197
	v_lshlrev_b32_e32 v201, v199, v201
	v_cndmask_b32_e64 v96, 0, v201, s[58:59]
	v_cndmask_b32_e64 v97, 0, v201, s[60:61]
	v_cndmask_b32_e64 v98, 0, v201, s[98:99]
	v_cndmask_b32_e64 v99, 0, v201, s[100:101]
	v_lshrrev_b32_e32 v8, 2, v252
	v_and_b32_e32 v9, 3, v252
	v_lshl_add_u32 v8, v8, 3, v9
	v_lshl_add_u32 v8, s5, 5, v8
	v_mul_u32_u24_e32 v8, 0x90, v8
	v_lshl_add_u32 v8, v253, 4, v8
	v_add_u32_e32 v8, 0x20900, v8
	v_add_u32_e32 v130, s64, v8
	v_add_u32_e32 v131, s71, v8
	v_and_b32_e32 v8, 0xff, v156
	v_lshrrev_b32_e32 v9, 3, v8
	v_mul_u32_u24_e32 v9, 0x90, v9
	v_and_b32_e32 v10, 7, v8
	v_lshl_add_u32 v9, v10, 4, v9
	v_add_u32_e32 v134, 0x20900, v9
	v_lshlrev_b32_e32 v154, 4, v8
	v_add_u32_e32 v155, 0x1000, v154
	v_min_u32_e32 v9, 23, v8
	v_add_u32_e32 v9, 0x200, v9
	v_lshlrev_b32_e32 v159, 4, v9
	v_lshrrev_b32_e32 v10, 3, v9
	v_mul_u32_u24_e32 v10, 0x90, v10
	v_and_b32_e32 v9, 7, v9
	v_lshl_add_u32 v10, v9, 4, v10
	v_add_u32_e32 v135, 0x20900, v10
	s_lshl_b32 s52, s6, 8
	s_add_i32 s52, s52, 0x20100
	v_lshl_add_u32 v183, v252, 3, s52
	s_lshl_b32 s52, s5, 7
	v_add_u32_e32 v182, s52, v183
	s_lshl_b32 s52, s5, 11
	s_lshl_b32 s9, s6, 5
	s_add_i32 s52, s52, s9
	s_add_i32 s52, s52, 0x100
	v_lshlrev_b32_e32 v8, 9, v253
	v_lshl_add_u32 v8, v252, 1, v8
	v_add_u32_e32 v116, s52, v8
	v_lshlrev_b32_e32 v117, 2, v252
	v_cmp_eq_u32_e64 s[10:11], 0, v253
	v_cmp_lt_u32_e64 s[16:17], 0, v253
	v_cmp_lt_u32_e64 s[20:21], 1, v253
	v_cmp_lt_u32_e64 s[22:23], 2, v253
	s_cmp_lg_u32 s5, 0
	s_cselect_b64 s[24:25], -1, 0
	v_mov_b32_e32 v180, 0
	s_add_u32 s26, s50, 0x0
	s_addc_u32 s27, s51, 0
	global_load_dwordx4 v[230:233], v154, s[26:27]
	global_load_dwordx4 v[234:237], v155, s[26:27]
	global_load_dwordx4 v[238:241], v159, s[26:27]
	s_add_u32 s26, s50, 0x2000
	s_addc_u32 s27, s51, 0
	global_load_dwordx4 v[146:149], v154, s[26:27]
	global_load_dwordx4 v[150:153], v155, s[26:27]
	global_load_dwordx4 v[160:163], v159, s[26:27]
	s_waitcnt vmcnt(0)
	ds_write_b128 v134, v[230:233]
	ds_write_b128 v134, v[234:237] offset:4608
	ds_write_b128 v135, v[238:241]
	s_add_u32 s26, s50, 0x4000
	s_addc_u32 s27, s51, 0
	global_load_dwordx4 v[230:233], v154, s[26:27]
	global_load_dwordx4 v[234:237], v155, s[26:27]
	global_load_dwordx4 v[238:241], v159, s[26:27]
	s_mov_b32 s4, 0
	s_waitcnt lgkmcnt(0)
	s_barrier
.Lrec2_loop_d0:
	ds_read_b128 v[198:201], v130 offset:0
	ds_read_b128 v[202:205], v131 offset:0
	ds_read_b128 v[206:209], v130 offset:144
	ds_read_b128 v[210:213], v131 offset:144
	ds_read_b128 v[214:217], v130 offset:288
	ds_read_b128 v[218:221], v131 offset:288
	ds_read_b128 v[222:225], v130 offset:432
	ds_read_b128 v[226:229], v131 offset:432
	s_waitcnt lgkmcnt(7)
	v_mfma_f32_16x16x32_bf16 v[100:103], v[198:201], v[20:23], 0
	v_mfma_f32_16x16x32_bf16 v[104:107], v[198:201], v[52:55], 0
	v_mfma_f32_16x16x32_bf16 v[108:111], v[198:201], v[84:87], 0
	s_waitcnt lgkmcnt(6)
	v_mfma_f32_16x16x32_bf16 v[100:103], v[202:205], v[24:27], v[100:103]
	v_mfma_f32_16x16x32_bf16 v[104:107], v[202:205], v[56:59], v[104:107]
	ds_read_b128 v[198:201], v130 offset:576
	ds_read_b128 v[202:205], v131 offset:576
	s_waitcnt lgkmcnt(7)
	v_mfma_f32_16x16x32_bf16 v[100:103], v[206:209], v[28:31], v[100:103]
	v_mfma_f32_16x16x32_bf16 v[104:107], v[206:209], v[60:63], v[104:107]
	v_mfma_f32_16x16x32_bf16 v[108:111], v[206:209], v[88:91], v[108:111]
	s_waitcnt lgkmcnt(6)
	v_mfma_f32_16x16x32_bf16 v[100:103], v[210:213], v[32:35], v[100:103]
	v_mfma_f32_16x16x32_bf16 v[104:107], v[210:213], v[64:67], v[104:107]
	ds_read_b128 v[206:209], v130 offset:720
	ds_read_b128 v[210:213], v131 offset:720
	s_waitcnt lgkmcnt(7)
	v_mfma_f32_16x16x32_bf16 v[100:103], v[214:217], v[36:39], v[100:103]
	v_mfma_f32_16x16x32_bf16 v[104:107], v[214:217], v[68:71], v[104:107]
	v_mfma_f32_16x16x32_bf16 v[108:111], v[214:217], v[92:95], v[108:111]
	s_waitcnt lgkmcnt(6)
	v_mfma_f32_16x16x32_bf16 v[100:103], v[218:221], v[40:43], v[100:103]
	v_mfma_f32_16x16x32_bf16 v[104:107], v[218:221], v[72:75], v[104:107]
	ds_read_b128 v[214:217], v130 offset:864
	ds_read_b128 v[218:221], v131 offset:864
	s_waitcnt lgkmcnt(7)
	v_mfma_f32_16x16x32_bf16 v[100:103], v[222:225], v[44:47], v[100:103]
	v_mfma_f32_16x16x32_bf16 v[104:107], v[222:225], v[76:79], v[104:107]
	v_mfma_f32_16x16x32_bf16 v[108:111], v[222:225], v[96:99], v[108:111]
	s_waitcnt lgkmcnt(6)
	v_mfma_f32_16x16x32_bf16 v[100:103], v[226:229], v[48:51], v[100:103]
	v_mfma_f32_16x16x32_bf16 v[104:107], v[226:229], v[80:83], v[104:107]
	ds_read_b128 v[222:225], v130 offset:1008
	ds_read_b128 v[226:229], v131 offset:1008
	s_waitcnt lgkmcnt(7)
	v_mfma_f32_16x16x32_bf16 v[112:115], v[198:201], v[20:23], 0
	v_mfma_f32_16x16x32_bf16 v[138:141], v[198:201], v[52:55], 0
	v_mfma_f32_16x16x32_bf16 v[142:145], v[198:201], v[84:87], 0
	s_waitcnt lgkmcnt(6)
	v_mfma_f32_16x16x32_bf16 v[112:115], v[202:205], v[24:27], v[112:115]
	v_mfma_f32_16x16x32_bf16 v[138:141], v[202:205], v[56:59], v[138:141]
	s_waitcnt lgkmcnt(5)
	v_mfma_f32_16x16x32_bf16 v[112:115], v[206:209], v[28:31], v[112:115]
	v_mfma_f32_16x16x32_bf16 v[138:141], v[206:209], v[60:63], v[138:141]
	v_mfma_f32_16x16x32_bf16 v[142:145], v[206:209], v[88:91], v[142:145]
	s_waitcnt lgkmcnt(4)
	v_mfma_f32_16x16x32_bf16 v[112:115], v[210:213], v[32:35], v[112:115]
	v_mfma_f32_16x16x32_bf16 v[138:141], v[210:213], v[64:67], v[138:141]
	s_waitcnt lgkmcnt(3)
	v_mfma_f32_16x16x32_bf16 v[112:115], v[214:217], v[36:39], v[112:115]
	v_mfma_f32_16x16x32_bf16 v[138:141], v[214:217], v[68:71], v[138:141]
	v_mfma_f32_16x16x32_bf16 v[142:145], v[214:217], v[92:95], v[142:145]
	s_waitcnt lgkmcnt(2)
	v_mfma_f32_16x16x32_bf16 v[112:115], v[218:221], v[40:43], v[112:115]
	v_mfma_f32_16x16x32_bf16 v[138:141], v[218:221], v[72:75], v[138:141]
	s_waitcnt lgkmcnt(1)
	v_mfma_f32_16x16x32_bf16 v[112:115], v[222:225], v[44:47], v[112:115]
	v_mfma_f32_16x16x32_bf16 v[138:141], v[222:225], v[76:79], v[138:141]
	v_mfma_f32_16x16x32_bf16 v[142:145], v[222:225], v[96:99], v[142:145]
	s_waitcnt lgkmcnt(0)
	v_mfma_f32_16x16x32_bf16 v[112:115], v[226:229], v[48:51], v[112:115]
	v_mfma_f32_16x16x32_bf16 v[138:141], v[226:229], v[80:83], v[138:141]
	s_waitcnt lgkmcnt(0)
	s_barrier
	s_waitcnt vmcnt(3)
	ds_write_b128 v134, v[146:149]
	ds_write_b128 v134, v[150:153] offset:4608
	ds_write_b128 v135, v[160:163]
	s_add_i32 s52, s4, 3
	s_min_u32 s52, s52, 31
	s_lshl_b32 s52, s52, 13
	s_add_u32 s26, s50, s52
	s_addc_u32 s27, s51, 0
	global_load_dwordx4 v[146:149], v154, s[26:27]
	global_load_dwordx4 v[150:153], v155, s[26:27]
	global_load_dwordx4 v[160:163], v159, s[26:27]
	v_add_f32_e32 v198, v128, v100
	v_add_f32_e32 v199, v128, v101
	v_add_f32_e32 v200, v128, v102
	v_add_f32_e32 v201, v128, v103
	v_add_f32_e32 v202, v128, v112
	v_add_f32_e32 v203, v128, v113
	v_add_f32_e32 v204, v128, v114
	v_add_f32_e32 v205, v128, v115
	v_add_f32_e32 v214, v178, v104
	v_add_f32_e32 v215, v178, v105
	v_add_f32_e32 v216, v178, v106
	v_add_f32_e32 v217, v178, v107
	v_add_f32_e32 v218, v178, v138
	v_add_f32_e32 v219, v178, v139
	v_add_f32_e32 v220, v178, v140
	v_add_f32_e32 v221, v178, v141
	v_exp_f32_e32 v198, v198
	v_exp_f32_e32 v199, v199
	v_exp_f32_e32 v200, v200
	v_exp_f32_e32 v201, v201
	v_exp_f32_e32 v202, v202
	v_exp_f32_e32 v203, v203
	v_exp_f32_e32 v204, v204
	v_exp_f32_e32 v205, v205
	v_exp_f32_e32 v214, v214
	v_exp_f32_e32 v215, v215
	v_exp_f32_e32 v216, v216
	v_exp_f32_e32 v217, v217
	v_exp_f32_e32 v218, v218
	v_exp_f32_e32 v219, v219
	v_exp_f32_e32 v220, v220
	v_exp_f32_e32 v221, v221
	v_add_f32_e32 v198, 1.0, v198
	v_add_f32_e32 v199, 1.0, v199
	v_add_f32_e32 v200, 1.0, v200
	v_add_f32_e32 v201, 1.0, v201
	v_add_f32_e32 v202, 1.0, v202
	v_add_f32_e32 v203, 1.0, v203
	v_add_f32_e32 v204, 1.0, v204
	v_add_f32_e32 v205, 1.0, v205
	v_add_f32_e32 v214, 1.0, v214
	v_add_f32_e32 v215, 1.0, v215
	v_add_f32_e32 v216, 1.0, v216
	v_add_f32_e32 v217, 1.0, v217
	v_add_f32_e32 v218, 1.0, v218
	v_add_f32_e32 v219, 1.0, v219
	v_add_f32_e32 v220, 1.0, v220
	v_add_f32_e32 v221, 1.0, v221
	v_rcp_f32_e32 v198, v198
	v_rcp_f32_e32 v199, v199
	v_rcp_f32_e32 v200, v200
	v_rcp_f32_e32 v201, v201
	v_rcp_f32_e32 v202, v202
	v_rcp_f32_e32 v203, v203
	v_rcp_f32_e32 v204, v204
	v_rcp_f32_e32 v205, v205
	v_add_f32_e32 v222, v133, v108
	v_add_f32_e32 v223, v133, v109
	v_add_f32_e32 v224, v133, v110
	v_add_f32_e32 v225, v133, v111
	v_add_f32_e32 v226, v133, v142
	v_add_f32_e32 v227, v133, v143
	v_add_f32_e32 v228, v133, v144
	v_add_f32_e32 v229, v133, v145
	v_mul_f32_e32 v198, v179, v198
	v_mul_f32_e32 v199, v179, v199
	v_mul_f32_e32 v200, v179, v200
	v_mul_f32_e32 v201, v179, v201
	v_mul_f32_e32 v202, v179, v202
	v_mul_f32_e32 v203, v179, v203
	v_mul_f32_e32 v204, v179, v204
	v_mul_f32_e32 v205, v179, v205
	v_exp_f32_e32 v120, v198
	v_exp_f32_e32 v121, v199
	v_exp_f32_e32 v122, v200
	v_exp_f32_e32 v123, v201
	v_exp_f32_e32 v124, v202
	v_exp_f32_e32 v125, v203
	v_exp_f32_e32 v126, v204
	v_exp_f32_e32 v127, v205
	s_nop 0
	v_fma_f32 v206, -v120, v120, 1.0
	v_fma_f32 v207, -v121, v121, 1.0
	v_fma_f32 v208, -v122, v122, 1.0
	v_fma_f32 v209, -v123, v123, 1.0
	v_fma_f32 v210, -v124, v124, 1.0
	v_fma_f32 v211, -v125, v125, 1.0
	v_fma_f32 v212, -v126, v126, 1.0
	v_fma_f32 v213, -v127, v127, 1.0
	v_max_f32_e32 v206, 0xda24260, v206
	v_max_f32_e32 v207, 0xda24260, v207
	v_max_f32_e32 v208, 0xda24260, v208
	v_max_f32_e32 v209, 0xda24260, v209
	v_max_f32_e32 v210, 0xda24260, v210
	v_max_f32_e32 v211, 0xda24260, v211
	v_max_f32_e32 v212, 0xda24260, v212
	v_max_f32_e32 v213, 0xda24260, v213
	v_mul_f32_e32 v198, v214, v206
	v_mul_f32_e32 v199, v215, v207
	v_mul_f32_e32 v200, v216, v208
	v_mul_f32_e32 v201, v217, v209
	v_mul_f32_e32 v202, v218, v210
	v_mul_f32_e32 v203, v219, v211
	v_mul_f32_e32 v204, v220, v212
	v_mul_f32_e32 v205, v221, v213
	v_mul_f32_e32 v214, v214, v198
	v_mul_f32_e32 v215, v215, v199
	v_mul_f32_e32 v216, v216, v200
	v_mul_f32_e32 v217, v217, v201
	v_mul_f32_e32 v218, v218, v202
	v_mul_f32_e32 v219, v219, v203
	v_mul_f32_e32 v220, v220, v204
	v_mul_f32_e32 v221, v221, v205
	v_rsq_f32_e32 v214, v214
	v_rsq_f32_e32 v215, v215
	v_rsq_f32_e32 v216, v216
	v_rsq_f32_e32 v217, v217
	v_rsq_f32_e32 v218, v218
	v_rsq_f32_e32 v219, v219
	v_rsq_f32_e32 v220, v220
	v_rsq_f32_e32 v221, v221
	v_mul_f32_e32 v222, v222, v206
	v_mul_f32_e32 v223, v223, v207
	v_mul_f32_e32 v224, v224, v208
	v_mul_f32_e32 v225, v225, v209
	v_mul_f32_e32 v226, v226, v210
	v_mul_f32_e32 v227, v227, v211
	v_mul_f32_e32 v228, v228, v212
	v_mul_f32_e32 v229, v229, v213
	s_nop 0
	v_mul_f32_e32 v170, v222, v214
	v_mul_f32_e32 v171, v223, v215
	v_mul_f32_e32 v172, v224, v216
	v_mul_f32_e32 v173, v225, v217
	v_mul_f32_e32 v174, v226, v218
	v_mul_f32_e32 v175, v227, v219
	v_mul_f32_e32 v176, v228, v220
	v_mul_f32_e32 v177, v229, v221
	v_mov_b32_e32 v198, v170
	v_mov_b32_e32 v199, v120
	v_fma_f32 v198, v121, v198, v171
	v_mul_f32_e32 v199, v199, v121
	v_fma_f32 v198, v122, v198, v172
	v_mul_f32_e32 v199, v199, v122
	v_fma_f32 v198, v123, v198, v173
	v_mul_f32_e32 v199, v199, v123
	v_fma_f32 v198, v124, v198, v174
	v_mul_f32_e32 v199, v199, v124
	v_fma_f32 v198, v125, v198, v175
	v_mul_f32_e32 v199, v199, v125
	v_fma_f32 v198, v126, v198, v176
	v_mul_f32_e32 v199, v199, v126
	v_fma_f32 v198, v127, v198, v177
	v_mul_f32_e32 v199, v199, v127
	ds_bpermute_b32 v164, v117, v199 offset:0
	ds_bpermute_b32 v246, v117, v198 offset:0
	ds_bpermute_b32 v165, v117, v199 offset:64
	ds_bpermute_b32 v247, v117, v198 offset:64
	ds_bpermute_b32 v166, v117, v199 offset:128
	ds_bpermute_b32 v248, v117, v198 offset:128
	ds_bpermute_b32 v167, v117, v199 offset:192
	ds_bpermute_b32 v249, v117, v198 offset:192
	s_waitcnt lgkmcnt(0)
	v_mov_b32_e32 v251, v246
	v_mov_b32_e32 v250, v164
	v_fma_f32 v251, v251, v165, v247
	v_mul_f32_e32 v250, v250, v165
	v_fma_f32 v251, v251, v166, v248
	v_mul_f32_e32 v250, v250, v166
	v_fma_f32 v251, v251, v167, v249
	v_mul_f32_e32 v250, v250, v167
	s_mov_b64 exec, s[10:11]
	ds_write_b64 v182, v[250:251] offset:0
	s_mov_b64 exec, -1
	s_waitcnt lgkmcnt(0)
	s_barrier
	ds_read2_b64 v[4:7], v183 offset0:0 offset1:16
	s_add_i32 s52, s4, 0
	s_lshl_b32 s52, s52, 12
	v_add_u32_e32 v197, s52, v116
	s_cmp_ge_u32 s4, 16
	s_cselect_b64 s[58:59], -1, 0
	ds_read_u16 v206, v197 offset:0
	ds_read_u16 v207, v197 offset:64
	ds_read_u16 v208, v197 offset:128
	ds_read_u16 v209, v197 offset:192
	ds_read_u16 v210, v197 offset:256
	ds_read_u16 v211, v197 offset:320
	ds_read_u16 v212, v197 offset:384
	ds_read_u16 v213, v197 offset:448
	s_waitcnt lgkmcnt(8)
	v_fma_f32 v198, v180, v4, v5
	v_cndmask_b32_e64 v199, v180, v198, s[24:25]
	v_fma_f32 v180, v198, v6, v7
	v_fma_f32 v200, v199, v164, v246
	v_cndmask_b32_e64 v199, v199, v200, s[16:17]
	v_fma_f32 v200, v199, v165, v247
	v_cndmask_b32_e64 v199, v199, v200, s[20:21]
	v_fma_f32 v200, v199, v166, v248
	v_cndmask_b32_e64 v199, v199, v200, s[22:23]
	v_fma_f32 v214, v120, v199, v170
	v_fma_f32 v215, v121, v214, v171
	v_fma_f32 v216, v122, v215, v172
	v_fma_f32 v217, v123, v216, v173
	v_fma_f32 v218, v124, v217, v174
	v_fma_f32 v219, v125, v218, v175
	v_fma_f32 v220, v126, v219, v176
	v_fma_f32 v221, v127, v220, v177
	s_waitcnt lgkmcnt(0)
	v_lshlrev_b32_e32 v206, 16, v206
	v_lshlrev_b32_e32 v207, 16, v207
	v_lshlrev_b32_e32 v208, 16, v208
	v_lshlrev_b32_e32 v209, 16, v209
	v_lshlrev_b32_e32 v210, 16, v210
	v_lshlrev_b32_e32 v211, 16, v211
	v_lshlrev_b32_e32 v212, 16, v212
	v_lshlrev_b32_e32 v213, 16, v213
	v_cndmask_b32_e64 v206, 0, v206, s[58:59]
	v_cndmask_b32_e64 v207, 0, v207, s[58:59]
	v_cndmask_b32_e64 v208, 0, v208, s[58:59]
	v_cndmask_b32_e64 v209, 0, v209, s[58:59]
	v_cndmask_b32_e64 v210, 0, v210, s[58:59]
	v_cndmask_b32_e64 v211, 0, v211, s[58:59]
	v_cndmask_b32_e64 v212, 0, v212, s[58:59]
	v_cndmask_b32_e64 v213, 0, v213, s[58:59]
	v_add_f32_e32 v214, v214, v206
	v_add_f32_e32 v215, v215, v207
	v_add_f32_e32 v216, v216, v208
	v_add_f32_e32 v217, v217, v209
	v_add_f32_e32 v218, v218, v210
	v_add_f32_e32 v219, v219, v211
	v_add_f32_e32 v220, v220, v212
	v_add_f32_e32 v221, v221, v213
	v_cvt_pk_bf16_f32 v206, v214, v215
	v_cvt_pk_bf16_f32 v208, v216, v217
	v_cvt_pk_bf16_f32 v210, v218, v219
	v_cvt_pk_bf16_f32 v212, v220, v221
	ds_write_b16 v197, v206 offset:0
	ds_write_b16_d16_hi v197, v206 offset:64
	ds_write_b16 v197, v208 offset:128
	ds_write_b16_d16_hi v197, v208 offset:192
	ds_write_b16 v197, v210 offset:256
	ds_write_b16_d16_hi v197, v210 offset:320
	ds_write_b16 v197, v212 offset:384
	ds_write_b16_d16_hi v197, v212 offset:448
	ds_read_b128 v[198:201], v130 offset:0
	ds_read_b128 v[202:205], v131 offset:0
	ds_read_b128 v[206:209], v130 offset:144
	ds_read_b128 v[210:213], v131 offset:144
	ds_read_b128 v[214:217], v130 offset:288
	ds_read_b128 v[218:221], v131 offset:288
	ds_read_b128 v[222:225], v130 offset:432
	ds_read_b128 v[226:229], v131 offset:432
	s_waitcnt lgkmcnt(7)
	v_mfma_f32_16x16x32_bf16 v[100:103], v[198:201], v[20:23], 0
	v_mfma_f32_16x16x32_bf16 v[104:107], v[198:201], v[52:55], 0
	v_mfma_f32_16x16x32_bf16 v[108:111], v[198:201], v[84:87], 0
	s_waitcnt lgkmcnt(6)
	v_mfma_f32_16x16x32_bf16 v[100:103], v[202:205], v[24:27], v[100:103]
	v_mfma_f32_16x16x32_bf16 v[104:107], v[202:205], v[56:59], v[104:107]
	ds_read_b128 v[198:201], v130 offset:576
	ds_read_b128 v[202:205], v131 offset:576
	s_waitcnt lgkmcnt(7)
	v_mfma_f32_16x16x32_bf16 v[100:103], v[206:209], v[28:31], v[100:103]
	v_mfma_f32_16x16x32_bf16 v[104:107], v[206:209], v[60:63], v[104:107]
	v_mfma_f32_16x16x32_bf16 v[108:111], v[206:209], v[88:91], v[108:111]
	s_waitcnt lgkmcnt(6)
	v_mfma_f32_16x16x32_bf16 v[100:103], v[210:213], v[32:35], v[100:103]
	v_mfma_f32_16x16x32_bf16 v[104:107], v[210:213], v[64:67], v[104:107]
	ds_read_b128 v[206:209], v130 offset:720
	ds_read_b128 v[210:213], v131 offset:720
	s_waitcnt lgkmcnt(7)
	v_mfma_f32_16x16x32_bf16 v[100:103], v[214:217], v[36:39], v[100:103]
	v_mfma_f32_16x16x32_bf16 v[104:107], v[214:217], v[68:71], v[104:107]
	v_mfma_f32_16x16x32_bf16 v[108:111], v[214:217], v[92:95], v[108:111]
	s_waitcnt lgkmcnt(6)
	v_mfma_f32_16x16x32_bf16 v[100:103], v[218:221], v[40:43], v[100:103]
	v_mfma_f32_16x16x32_bf16 v[104:107], v[218:221], v[72:75], v[104:107]
	ds_read_b128 v[214:217], v130 offset:864
	ds_read_b128 v[218:221], v131 offset:864
	s_waitcnt lgkmcnt(7)
	v_mfma_f32_16x16x32_bf16 v[100:103], v[222:225], v[44:47], v[100:103]
	v_mfma_f32_16x16x32_bf16 v[104:107], v[222:225], v[76:79], v[104:107]
	v_mfma_f32_16x16x32_bf16 v[108:111], v[222:225], v[96:99], v[108:111]
	s_waitcnt lgkmcnt(6)
	v_mfma_f32_16x16x32_bf16 v[100:103], v[226:229], v[48:51], v[100:103]
	v_mfma_f32_16x16x32_bf16 v[104:107], v[226:229], v[80:83], v[104:107]
	ds_read_b128 v[222:225], v130 offset:1008
	ds_read_b128 v[226:229], v131 offset:1008
	s_waitcnt lgkmcnt(7)
	v_mfma_f32_16x16x32_bf16 v[112:115], v[198:201], v[20:23], 0
	v_mfma_f32_16x16x32_bf16 v[138:141], v[198:201], v[52:55], 0
	v_mfma_f32_16x16x32_bf16 v[142:145], v[198:201], v[84:87], 0
	s_waitcnt lgkmcnt(6)
	v_mfma_f32_16x16x32_bf16 v[112:115], v[202:205], v[24:27], v[112:115]
	v_mfma_f32_16x16x32_bf16 v[138:141], v[202:205], v[56:59], v[138:141]
	s_waitcnt lgkmcnt(5)
	v_mfma_f32_16x16x32_bf16 v[112:115], v[206:209], v[28:31], v[112:115]
	v_mfma_f32_16x16x32_bf16 v[138:141], v[206:209], v[60:63], v[138:141]
	v_mfma_f32_16x16x32_bf16 v[142:145], v[206:209], v[88:91], v[142:145]
	s_waitcnt lgkmcnt(4)
	v_mfma_f32_16x16x32_bf16 v[112:115], v[210:213], v[32:35], v[112:115]
	v_mfma_f32_16x16x32_bf16 v[138:141], v[210:213], v[64:67], v[138:141]
	s_waitcnt lgkmcnt(3)
	v_mfma_f32_16x16x32_bf16 v[112:115], v[214:217], v[36:39], v[112:115]
	v_mfma_f32_16x16x32_bf16 v[138:141], v[214:217], v[68:71], v[138:141]
	v_mfma_f32_16x16x32_bf16 v[142:145], v[214:217], v[92:95], v[142:145]
	s_waitcnt lgkmcnt(2)
	v_mfma_f32_16x16x32_bf16 v[112:115], v[218:221], v[40:43], v[112:115]
	v_mfma_f32_16x16x32_bf16 v[138:141], v[218:221], v[72:75], v[138:141]
	s_waitcnt lgkmcnt(1)
	v_mfma_f32_16x16x32_bf16 v[112:115], v[222:225], v[44:47], v[112:115]
	v_mfma_f32_16x16x32_bf16 v[138:141], v[222:225], v[76:79], v[138:141]
	v_mfma_f32_16x16x32_bf16 v[142:145], v[222:225], v[96:99], v[142:145]
	s_waitcnt lgkmcnt(0)
	v_mfma_f32_16x16x32_bf16 v[112:115], v[226:229], v[48:51], v[112:115]
	v_mfma_f32_16x16x32_bf16 v[138:141], v[226:229], v[80:83], v[138:141]
	s_waitcnt lgkmcnt(0)
	s_barrier
	s_waitcnt vmcnt(3)
	ds_write_b128 v134, v[230:233]
	ds_write_b128 v134, v[234:237] offset:4608
	ds_write_b128 v135, v[238:241]
	s_add_i32 s52, s4, 4
	s_min_u32 s52, s52, 31
	s_lshl_b32 s52, s52, 13
	s_add_u32 s26, s50, s52
	s_addc_u32 s27, s51, 0
	global_load_dwordx4 v[230:233], v154, s[26:27]
	global_load_dwordx4 v[234:237], v155, s[26:27]
	global_load_dwordx4 v[238:241], v159, s[26:27]
	v_add_f32_e32 v198, v128, v100
	v_add_f32_e32 v199, v128, v101
	v_add_f32_e32 v200, v128, v102
	v_add_f32_e32 v201, v128, v103
	v_add_f32_e32 v202, v128, v112
	v_add_f32_e32 v203, v128, v113
	v_add_f32_e32 v204, v128, v114
	v_add_f32_e32 v205, v128, v115
	v_add_f32_e32 v214, v178, v104
	v_add_f32_e32 v215, v178, v105
	v_add_f32_e32 v216, v178, v106
	v_add_f32_e32 v217, v178, v107
	v_add_f32_e32 v218, v178, v138
	v_add_f32_e32 v219, v178, v139
	v_add_f32_e32 v220, v178, v140
	v_add_f32_e32 v221, v178, v141
	v_exp_f32_e32 v198, v198
	v_exp_f32_e32 v199, v199
	v_exp_f32_e32 v200, v200
	v_exp_f32_e32 v201, v201
	v_exp_f32_e32 v202, v202
	v_exp_f32_e32 v203, v203
	v_exp_f32_e32 v204, v204
	v_exp_f32_e32 v205, v205
	v_exp_f32_e32 v214, v214
	v_exp_f32_e32 v215, v215
	v_exp_f32_e32 v216, v216
	v_exp_f32_e32 v217, v217
	v_exp_f32_e32 v218, v218
	v_exp_f32_e32 v219, v219
	v_exp_f32_e32 v220, v220
	v_exp_f32_e32 v221, v221
	v_add_f32_e32 v198, 1.0, v198
	v_add_f32_e32 v199, 1.0, v199
	v_add_f32_e32 v200, 1.0, v200
	v_add_f32_e32 v201, 1.0, v201
	v_add_f32_e32 v202, 1.0, v202
	v_add_f32_e32 v203, 1.0, v203
	v_add_f32_e32 v204, 1.0, v204
	v_add_f32_e32 v205, 1.0, v205
	v_add_f32_e32 v214, 1.0, v214
	v_add_f32_e32 v215, 1.0, v215
	v_add_f32_e32 v216, 1.0, v216
	v_add_f32_e32 v217, 1.0, v217
	v_add_f32_e32 v218, 1.0, v218
	v_add_f32_e32 v219, 1.0, v219
	v_add_f32_e32 v220, 1.0, v220
	v_add_f32_e32 v221, 1.0, v221
	v_rcp_f32_e32 v198, v198
	v_rcp_f32_e32 v199, v199
	v_rcp_f32_e32 v200, v200
	v_rcp_f32_e32 v201, v201
	v_rcp_f32_e32 v202, v202
	v_rcp_f32_e32 v203, v203
	v_rcp_f32_e32 v204, v204
	v_rcp_f32_e32 v205, v205
	v_add_f32_e32 v222, v133, v108
	v_add_f32_e32 v223, v133, v109
	v_add_f32_e32 v224, v133, v110
	v_add_f32_e32 v225, v133, v111
	v_add_f32_e32 v226, v133, v142
	v_add_f32_e32 v227, v133, v143
	v_add_f32_e32 v228, v133, v144
	v_add_f32_e32 v229, v133, v145
	v_mul_f32_e32 v198, v179, v198
	v_mul_f32_e32 v199, v179, v199
	v_mul_f32_e32 v200, v179, v200
	v_mul_f32_e32 v201, v179, v201
	v_mul_f32_e32 v202, v179, v202
	v_mul_f32_e32 v203, v179, v203
	v_mul_f32_e32 v204, v179, v204
	v_mul_f32_e32 v205, v179, v205
	v_exp_f32_e32 v120, v198
	v_exp_f32_e32 v121, v199
	v_exp_f32_e32 v122, v200
	v_exp_f32_e32 v123, v201
	v_exp_f32_e32 v124, v202
	v_exp_f32_e32 v125, v203
	v_exp_f32_e32 v126, v204
	v_exp_f32_e32 v127, v205
	s_nop 0
	v_fma_f32 v206, -v120, v120, 1.0
	v_fma_f32 v207, -v121, v121, 1.0
	v_fma_f32 v208, -v122, v122, 1.0
	v_fma_f32 v209, -v123, v123, 1.0
	v_fma_f32 v210, -v124, v124, 1.0
	v_fma_f32 v211, -v125, v125, 1.0
	v_fma_f32 v212, -v126, v126, 1.0
	v_fma_f32 v213, -v127, v127, 1.0
	v_max_f32_e32 v206, 0xda24260, v206
	v_max_f32_e32 v207, 0xda24260, v207
	v_max_f32_e32 v208, 0xda24260, v208
	v_max_f32_e32 v209, 0xda24260, v209
	v_max_f32_e32 v210, 0xda24260, v210
	v_max_f32_e32 v211, 0xda24260, v211
	v_max_f32_e32 v212, 0xda24260, v212
	v_max_f32_e32 v213, 0xda24260, v213
	v_mul_f32_e32 v198, v214, v206
	v_mul_f32_e32 v199, v215, v207
	v_mul_f32_e32 v200, v216, v208
	v_mul_f32_e32 v201, v217, v209
	v_mul_f32_e32 v202, v218, v210
	v_mul_f32_e32 v203, v219, v211
	v_mul_f32_e32 v204, v220, v212
	v_mul_f32_e32 v205, v221, v213
	v_mul_f32_e32 v214, v214, v198
	v_mul_f32_e32 v215, v215, v199
	v_mul_f32_e32 v216, v216, v200
	v_mul_f32_e32 v217, v217, v201
	v_mul_f32_e32 v218, v218, v202
	v_mul_f32_e32 v219, v219, v203
	v_mul_f32_e32 v220, v220, v204
	v_mul_f32_e32 v221, v221, v205
	v_rsq_f32_e32 v214, v214
	v_rsq_f32_e32 v215, v215
	v_rsq_f32_e32 v216, v216
	v_rsq_f32_e32 v217, v217
	v_rsq_f32_e32 v218, v218
	v_rsq_f32_e32 v219, v219
	v_rsq_f32_e32 v220, v220
	v_rsq_f32_e32 v221, v221
	v_mul_f32_e32 v222, v222, v206
	v_mul_f32_e32 v223, v223, v207
	v_mul_f32_e32 v224, v224, v208
	v_mul_f32_e32 v225, v225, v209
	v_mul_f32_e32 v226, v226, v210
	v_mul_f32_e32 v227, v227, v211
	v_mul_f32_e32 v228, v228, v212
	v_mul_f32_e32 v229, v229, v213
	s_nop 0
	v_mul_f32_e32 v170, v222, v214
	v_mul_f32_e32 v171, v223, v215
	v_mul_f32_e32 v172, v224, v216
	v_mul_f32_e32 v173, v225, v217
	v_mul_f32_e32 v174, v226, v218
	v_mul_f32_e32 v175, v227, v219
	v_mul_f32_e32 v176, v228, v220
	v_mul_f32_e32 v177, v229, v221
	v_mov_b32_e32 v198, v170
	v_mov_b32_e32 v199, v120
	v_fma_f32 v198, v121, v198, v171
	v_mul_f32_e32 v199, v199, v121
	v_fma_f32 v198, v122, v198, v172
	v_mul_f32_e32 v199, v199, v122
	v_fma_f32 v198, v123, v198, v173
	v_mul_f32_e32 v199, v199, v123
	v_fma_f32 v198, v124, v198, v174
	v_mul_f32_e32 v199, v199, v124
	v_fma_f32 v198, v125, v198, v175
	v_mul_f32_e32 v199, v199, v125
	v_fma_f32 v198, v126, v198, v176
	v_mul_f32_e32 v199, v199, v126
	v_fma_f32 v198, v127, v198, v177
	v_mul_f32_e32 v199, v199, v127
	ds_bpermute_b32 v164, v117, v199 offset:0
	ds_bpermute_b32 v246, v117, v198 offset:0
	ds_bpermute_b32 v165, v117, v199 offset:64
	ds_bpermute_b32 v247, v117, v198 offset:64
	ds_bpermute_b32 v166, v117, v199 offset:128
	ds_bpermute_b32 v248, v117, v198 offset:128
	ds_bpermute_b32 v167, v117, v199 offset:192
	ds_bpermute_b32 v249, v117, v198 offset:192
	s_waitcnt lgkmcnt(0)
	v_mov_b32_e32 v251, v246
	v_mov_b32_e32 v250, v164
	v_fma_f32 v251, v251, v165, v247
	v_mul_f32_e32 v250, v250, v165
	v_fma_f32 v251, v251, v166, v248
	v_mul_f32_e32 v250, v250, v166
	v_fma_f32 v251, v251, v167, v249
	v_mul_f32_e32 v250, v250, v167
	s_mov_b64 exec, s[10:11]
	ds_write_b64 v182, v[250:251] offset:1024
	s_mov_b64 exec, -1
	s_waitcnt lgkmcnt(0)
	s_barrier
	ds_read2_b64 v[4:7], v183 offset0:128 offset1:144
	s_add_i32 s52, s4, 1
	s_lshl_b32 s52, s52, 12
	v_add_u32_e32 v197, s52, v116
	s_cmp_ge_u32 s4, 16
	s_cselect_b64 s[58:59], -1, 0
	ds_read_u16 v206, v197 offset:0
	ds_read_u16 v207, v197 offset:64
	ds_read_u16 v208, v197 offset:128
	ds_read_u16 v209, v197 offset:192
	ds_read_u16 v210, v197 offset:256
	ds_read_u16 v211, v197 offset:320
	ds_read_u16 v212, v197 offset:384
	ds_read_u16 v213, v197 offset:448
	s_waitcnt lgkmcnt(8)
	v_fma_f32 v198, v180, v4, v5
	v_cndmask_b32_e64 v199, v180, v198, s[24:25]
	v_fma_f32 v180, v198, v6, v7
	v_fma_f32 v200, v199, v164, v246
	v_cndmask_b32_e64 v199, v199, v200, s[16:17]
	v_fma_f32 v200, v199, v165, v247
	v_cndmask_b32_e64 v199, v199, v200, s[20:21]
	v_fma_f32 v200, v199, v166, v248
	v_cndmask_b32_e64 v199, v199, v200, s[22:23]
	v_fma_f32 v214, v120, v199, v170
	v_fma_f32 v215, v121, v214, v171
	v_fma_f32 v216, v122, v215, v172
	v_fma_f32 v217, v123, v216, v173
	v_fma_f32 v218, v124, v217, v174
	v_fma_f32 v219, v125, v218, v175
	v_fma_f32 v220, v126, v219, v176
	v_fma_f32 v221, v127, v220, v177
	s_waitcnt lgkmcnt(0)
	v_lshlrev_b32_e32 v206, 16, v206
	v_lshlrev_b32_e32 v207, 16, v207
	v_lshlrev_b32_e32 v208, 16, v208
	v_lshlrev_b32_e32 v209, 16, v209
	v_lshlrev_b32_e32 v210, 16, v210
	v_lshlrev_b32_e32 v211, 16, v211
	v_lshlrev_b32_e32 v212, 16, v212
	v_lshlrev_b32_e32 v213, 16, v213
	v_cndmask_b32_e64 v206, 0, v206, s[58:59]
	v_cndmask_b32_e64 v207, 0, v207, s[58:59]
	v_cndmask_b32_e64 v208, 0, v208, s[58:59]
	v_cndmask_b32_e64 v209, 0, v209, s[58:59]
	v_cndmask_b32_e64 v210, 0, v210, s[58:59]
	v_cndmask_b32_e64 v211, 0, v211, s[58:59]
	v_cndmask_b32_e64 v212, 0, v212, s[58:59]
	v_cndmask_b32_e64 v213, 0, v213, s[58:59]
	v_add_f32_e32 v214, v214, v206
	v_add_f32_e32 v215, v215, v207
	v_add_f32_e32 v216, v216, v208
	v_add_f32_e32 v217, v217, v209
	v_add_f32_e32 v218, v218, v210
	v_add_f32_e32 v219, v219, v211
	v_add_f32_e32 v220, v220, v212
	v_add_f32_e32 v221, v221, v213
	v_cvt_pk_bf16_f32 v206, v214, v215
	v_cvt_pk_bf16_f32 v208, v216, v217
	v_cvt_pk_bf16_f32 v210, v218, v219
	v_cvt_pk_bf16_f32 v212, v220, v221
	ds_write_b16 v197, v206 offset:0
	ds_write_b16_d16_hi v197, v206 offset:64
	ds_write_b16 v197, v208 offset:128
	ds_write_b16_d16_hi v197, v208 offset:192
	ds_write_b16 v197, v210 offset:256
	ds_write_b16_d16_hi v197, v210 offset:320
	ds_write_b16 v197, v212 offset:384
	ds_write_b16_d16_hi v197, v212 offset:448
	s_add_i32 s4, s4, 2
	s_cmp_lt_u32 s4, 32
	s_cbranch_scc1 .Lrec2_loop_d0
	s_barrier
	s_branch .Lrec2_done
.Lrec2_bwd:
	v_and_b32_e32 v252, 15, v157
	v_lshrrev_b32_e32 v253, 4, v157
	s_bfe_u32 s5, s85, 0x10006
	s_bfe_u32 s6, s85, 0x10007
	s_and_b32 s8, s84, 1
	v_readlane_b32 s26, v254, 13
	v_readlane_b32 s27, v254, 14
	s_nop 3
	s_lshl_b32 s9, s70, 2
	s_add_i32 s9, s9, 2
	s_lshl_b32 s52, s9, 15
	s_add_u32 s26, s26, 0x100000
	s_addc_u32 s27, s27, 0
	s_add_u32 s26, s26, s52
	s_addc_u32 s27, s27, 0
	v_add_u32_e32 v8, s34, v252
	v_lshlrev_b32_e32 v9, 7, v8
	v_lshl_add_u32 v9, v253, 4, v9
	s_lshl_b32 s64, s8, 6
	s_xor_b32 s71, s64, 64
	v_add_u32_e32 v10, s64, v9
	v_add_u32_e32 v255, s71, v9
	s_add_u32 s38, s26, 0x0
	s_addc_u32 s39, s27, 0
	global_load_dwordx4 v[20:23], v10, s[38:39]
	global_load_dwordx4 v[24:27], v255, s[38:39]
	s_add_u32 s38, s26, 0x2000
	s_addc_u32 s39, s27, 0
	global_load_dwordx4 v[28:31], v10, s[38:39]
	global_load_dwordx4 v[32:35], v255, s[38:39]
	s_add_u32 s38, s26, 0x4000
	s_addc_u32 s39, s27, 0
	global_load_dwordx4 v[36:39], v10, s[38:39]
	global_load_dwordx4 v[40:43], v255, s[38:39]
	s_add_u32 s38, s26, 0x6000
	s_addc_u32 s39, s27, 0
	global_load_dwordx4 v[44:47], v10, s[38:39]
	global_load_dwordx4 v[48:51], v255, s[38:39]
	s_add_u32 s38, s26, 0x8000
	s_addc_u32 s39, s27, 0
	global_load_dwordx4 v[52:55], v10, s[38:39]
	global_load_dwordx4 v[56:59], v255, s[38:39]
	s_add_u32 s38, s26, 0xa000
	s_addc_u32 s39, s27, 0
	global_load_dwordx4 v[60:63], v10, s[38:39]
	global_load_dwordx4 v[64:67], v255, s[38:39]
	s_add_u32 s38, s26, 0xc000
	s_addc_u32 s39, s27, 0
	global_load_dwordx4 v[68:71], v10, s[38:39]
	global_load_dwordx4 v[72:75], v255, s[38:39]
	s_add_u32 s38, s26, 0xe000
	s_addc_u32 s39, s27, 0
	global_load_dwordx4 v[76:79], v10, s[38:39]
	global_load_dwordx4 v[80:83], v255, s[38:39]
	s_lshl_b32 s52, s9, 8
	s_add_i32 s52, s52, 0x15240
	v_lshlrev_b32_e32 v8, 2, v8
	v_add_u32_e32 v9, s52, v8
	global_load_dword v128, v9, s[90:91]
	global_load_dword v178, v9, s[90:91] offset:256
	s_lshl_b32 s52, s70, 8
	s_add_i32 s52, s52, 0x13240
	v_add_u32_e32 v9, s52, v8
	global_load_dword v179, v9, s[90:91]
	v_lshlrev_b32_e32 v198, 3, v253
	v_sub_u32_e32 v198, v252, v198
	v_lshl_add_u32 v198, s6, 4, v198
	v_cmp_gt_u32_e32 vcc, 8, v198
	v_and_b32_e32 v199, 1, v198
	v_lshlrev_b32_e32 v199, 4, v199
	v_lshrrev_b32_e32 v200, 1, v198
	s_nop 1
	v_cndmask_b32_e32 v200, 7, v200, vcc
	v_cmp_eq_u32_e64 s[58:59], 0, v200
	v_cmp_eq_u32_e64 s[60:61], 1, v200
	v_cmp_eq_u32_e64 s[98:99], 2, v200
	v_cmp_eq_u32_e64 s[100:101], 3, v200
	s_nop 1
	v_lshrrev_b32_e32 v201, 16, v184
	v_lshlrev_b32_e32 v201, v199, v201
	v_cndmask_b32_e64 v84, 0, v201, s[58:59]
	v_cndmask_b32_e64 v85, 0, v201, s[60:61]
	v_cndmask_b32_e64 v86, 0, v201, s[98:99]
	v_cndmask_b32_e64 v87, 0, v201, s[100:101]
	v_lshrrev_b32_e32 v201, 16, v185
	v_lshlrev_b32_e32 v201, v199, v201
	v_cndmask_b32_e64 v88, 0, v201, s[58:59]
	v_cndmask_b32_e64 v89, 0, v201, s[60:61]
	v_cndmask_b32_e64 v90, 0, v201, s[98:99]
	v_cndmask_b32_e64 v91, 0, v201, s[100:101]
	v_lshrrev_b32_e32 v201, 16, v195
	v_lshlrev_b32_e32 v201, v199, v201
	v_cndmask_b32_e64 v92, 0, v201, s[58:59]
	v_cndmask_b32_e64 v93, 0, v201, s[60:61]
	v_cndmask_b32_e64 v94, 0, v201, s[98:99]
	v_cndmask_b32_e64 v95, 0, v201, s[100:101]
	v_lshrrev_b32_e32 v201, 16, v197
	v_lshlrev_b32_e32 v201, v199, v201
	v_cndmask_b32_e64 v96, 0, v201, s[58:59]
	v_cndmask_b32_e64 v97, 0, v201, s[60:61]
	v_cndmask_b32_e64 v98, 0, v201, s[98:99]
	v_cndmask_b32_e64 v99, 0, v201, s[100:101]
	v_lshrrev_b32_e32 v8, 2, v252
	v_and_b32_e32 v9, 3, v252
	v_lshl_add_u32 v8, v8, 3, v9
	v_lshl_add_u32 v8, s5, 5, v8
	v_mul_u32_u24_e32 v8, 0x90, v8
	v_lshl_add_u32 v8, v253, 4, v8
	v_add_u32_e32 v8, 0x22f00, v8
	v_add_u32_e32 v130, s64, v8
	v_add_u32_e32 v131, s71, v8
	v_and_b32_e32 v8, 0xff, v156
	v_lshrrev_b32_e32 v9, 3, v8
	v_mul_u32_u24_e32 v9, 0x90, v9
	v_and_b32_e32 v10, 7, v8
	v_lshl_add_u32 v9, v10, 4, v9
	v_add_u32_e32 v134, 0x22f00, v9
	v_lshlrev_b32_e32 v154, 4, v8
	v_add_u32_e32 v155, 0x1000, v154
	v_min_u32_e32 v9, 23, v8
	v_add_u32_e32 v9, 0x200, v9
	v_lshlrev_b32_e32 v159, 4, v9
	v_lshrrev_b32_e32 v10, 3, v9
	v_mul_u32_u24_e32 v10, 0x90, v10
	v_and_b32_e32 v9, 7, v9
	v_lshl_add_u32 v10, v9, 4, v10
	v_add_u32_e32 v135, 0x22f00, v10
	s_lshl_b32 s52, s6, 8
	s_add_i32 s52, s52, 0x20300
	v_lshl_add_u32 v183, v252, 3, s52
	s_lshl_b32 s52, s5, 7
	v_add_u32_e32 v182, s52, v183
	s_lshl_b32 s52, s5, 11
	s_lshl_b32 s9, s6, 5
	s_add_i32 s52, s52, s9
	s_add_i32 s52, s52, 0x100
	v_lshlrev_b32_e32 v8, 9, v253
	v_lshl_add_u32 v8, v252, 1, v8
	v_add_u32_e32 v116, s52, v8
	v_lshlrev_b32_e32 v117, 2, v252
	v_cmp_eq_u32_e64 s[10:11], 0, v253
	v_cmp_gt_u32_e64 s[16:17], 3, v253
	v_cmp_gt_u32_e64 s[20:21], 2, v253
	v_cmp_gt_u32_e64 s[22:23], 1, v253
	s_cmp_eq_u32 s5, 0
	s_cselect_b64 s[24:25], -1, 0
	v_mov_b32_e32 v180, 0
	s_add_u32 s26, s50, 0x3e000
	s_addc_u32 s27, s51, 0
	global_load_dwordx4 v[230:233], v154, s[26:27]
	global_load_dwordx4 v[234:237], v155, s[26:27]
	global_load_dwordx4 v[238:241], v159, s[26:27]
	s_add_u32 s26, s50, 0x3c000
	s_addc_u32 s27, s51, 0
	global_load_dwordx4 v[146:149], v154, s[26:27]
	global_load_dwordx4 v[150:153], v155, s[26:27]
	global_load_dwordx4 v[160:163], v159, s[26:27]
	s_waitcnt vmcnt(0)
	ds_write_b128 v134, v[230:233]
	ds_write_b128 v134, v[234:237] offset:4608
	ds_write_b128 v135, v[238:241]
	s_add_u32 s26, s50, 0x3a000
	s_addc_u32 s27, s51, 0
	global_load_dwordx4 v[230:233], v154, s[26:27]
	global_load_dwordx4 v[234:237], v155, s[26:27]
	global_load_dwordx4 v[238:241], v159, s[26:27]
	s_mov_b32 s4, 0
	s_waitcnt lgkmcnt(0)
	s_barrier
	s_barrier
.Lrec2_loop_d1:
	ds_read_b128 v[198:201], v130 offset:0
	ds_read_b128 v[202:205], v131 offset:0
	ds_read_b128 v[206:209], v130 offset:144
	ds_read_b128 v[210:213], v131 offset:144
	ds_read_b128 v[214:217], v130 offset:288
	ds_read_b128 v[218:221], v131 offset:288
	ds_read_b128 v[222:225], v130 offset:432
	ds_read_b128 v[226:229], v131 offset:432
	s_waitcnt lgkmcnt(7)
	v_mfma_f32_16x16x32_bf16 v[100:103], v[198:201], v[20:23], 0
	v_mfma_f32_16x16x32_bf16 v[104:107], v[198:201], v[52:55], 0
	v_mfma_f32_16x16x32_bf16 v[108:111], v[198:201], v[84:87], 0
	s_waitcnt lgkmcnt(6)
	v_mfma_f32_16x16x32_bf16 v[100:103], v[202:205], v[24:27], v[100:103]
	v_mfma_f32_16x16x32_bf16 v[104:107], v[202:205], v[56:59], v[104:107]
	ds_read_b128 v[198:201], v130 offset:576
	ds_read_b128 v[202:205], v131 offset:576
	s_waitcnt lgkmcnt(7)
	v_mfma_f32_16x16x32_bf16 v[100:103], v[206:209], v[28:31], v[100:103]
	v_mfma_f32_16x16x32_bf16 v[104:107], v[206:209], v[60:63], v[104:107]
	v_mfma_f32_16x16x32_bf16 v[108:111], v[206:209], v[88:91], v[108:111]
	s_waitcnt lgkmcnt(6)
	v_mfma_f32_16x16x32_bf16 v[100:103], v[210:213], v[32:35], v[100:103]
	v_mfma_f32_16x16x32_bf16 v[104:107], v[210:213], v[64:67], v[104:107]
	ds_read_b128 v[206:209], v130 offset:720
	ds_read_b128 v[210:213], v131 offset:720
	s_waitcnt lgkmcnt(7)
	v_mfma_f32_16x16x32_bf16 v[100:103], v[214:217], v[36:39], v[100:103]
	v_mfma_f32_16x16x32_bf16 v[104:107], v[214:217], v[68:71], v[104:107]
	v_mfma_f32_16x16x32_bf16 v[108:111], v[214:217], v[92:95], v[108:111]
	s_waitcnt lgkmcnt(6)
	v_mfma_f32_16x16x32_bf16 v[100:103], v[218:221], v[40:43], v[100:103]
	v_mfma_f32_16x16x32_bf16 v[104:107], v[218:221], v[72:75], v[104:107]
	ds_read_b128 v[214:217], v130 offset:864
	ds_read_b128 v[218:221], v131 offset:864
	s_waitcnt lgkmcnt(7)
	v_mfma_f32_16x16x32_bf16 v[100:103], v[222:225], v[44:47], v[100:103]
	v_mfma_f32_16x16x32_bf16 v[104:107], v[222:225], v[76:79], v[104:107]
	v_mfma_f32_16x16x32_bf16 v[108:111], v[222:225], v[96:99], v[108:111]
	s_waitcnt lgkmcnt(6)
	v_mfma_f32_16x16x32_bf16 v[100:103], v[226:229], v[48:51], v[100:103]
	v_mfma_f32_16x16x32_bf16 v[104:107], v[226:229], v[80:83], v[104:107]
	ds_read_b128 v[222:225], v130 offset:1008
	ds_read_b128 v[226:229], v131 offset:1008
	s_waitcnt lgkmcnt(7)
	v_mfma_f32_16x16x32_bf16 v[112:115], v[198:201], v[20:23], 0
	v_mfma_f32_16x16x32_bf16 v[138:141], v[198:201], v[52:55], 0
	v_mfma_f32_16x16x32_bf16 v[142:145], v[198:201], v[84:87], 0
	s_waitcnt lgkmcnt(6)
	v_mfma_f32_16x16x32_bf16 v[112:115], v[202:205], v[24:27], v[112:115]
	v_mfma_f32_16x16x32_bf16 v[138:141], v[202:205], v[56:59], v[138:141]
	s_waitcnt lgkmcnt(5)
	v_mfma_f32_16x16x32_bf16 v[112:115], v[206:209], v[28:31], v[112:115]
	v_mfma_f32_16x16x32_bf16 v[138:141], v[206:209], v[60:63], v[138:141]
	v_mfma_f32_16x16x32_bf16 v[142:145], v[206:209], v[88:91], v[142:145]
	s_waitcnt lgkmcnt(4)
	v_mfma_f32_16x16x32_bf16 v[112:115], v[210:213], v[32:35], v[112:115]
	v_mfma_f32_16x16x32_bf16 v[138:141], v[210:213], v[64:67], v[138:141]
	s_waitcnt lgkmcnt(3)
	v_mfma_f32_16x16x32_bf16 v[112:115], v[214:217], v[36:39], v[112:115]
	v_mfma_f32_16x16x32_bf16 v[138:141], v[214:217], v[68:71], v[138:141]
	v_mfma_f32_16x16x32_bf16 v[142:145], v[214:217], v[92:95], v[142:145]
	s_waitcnt lgkmcnt(2)
	v_mfma_f32_16x16x32_bf16 v[112:115], v[218:221], v[40:43], v[112:115]
	v_mfma_f32_16x16x32_bf16 v[138:141], v[218:221], v[72:75], v[138:141]
	s_waitcnt lgkmcnt(1)
	v_mfma_f32_16x16x32_bf16 v[112:115], v[222:225], v[44:47], v[112:115]
	v_mfma_f32_16x16x32_bf16 v[138:141], v[222:225], v[76:79], v[138:141]
	v_mfma_f32_16x16x32_bf16 v[142:145], v[222:225], v[96:99], v[142:145]
	s_waitcnt lgkmcnt(0)
	v_mfma_f32_16x16x32_bf16 v[112:115], v[226:229], v[48:51], v[112:115]
	v_mfma_f32_16x16x32_bf16 v[138:141], v[226:229], v[80:83], v[138:141]
	s_waitcnt lgkmcnt(0)
	s_barrier
	s_waitcnt vmcnt(3)
	ds_write_b128 v134, v[146:149]
	ds_write_b128 v134, v[150:153] offset:4608
	ds_write_b128 v135, v[160:163]
	s_add_i32 s52, s4, 3
	s_min_u32 s52, s52, 31
	s_sub_i32 s52, 31, s52
	s_lshl_b32 s52, s52, 13
	s_add_u32 s26, s50, s52
	s_addc_u32 s27, s51, 0
	global_load_dwordx4 v[146:149], v154, s[26:27]
	global_load_dwordx4 v[150:153], v155, s[26:27]
	global_load_dwordx4 v[160:163], v159, s[26:27]
	v_add_f32_e32 v198, v128, v100
	v_add_f32_e32 v199, v128, v101
	v_add_f32_e32 v200, v128, v102
	v_add_f32_e32 v201, v128, v103
	v_add_f32_e32 v202, v128, v112
	v_add_f32_e32 v203, v128, v113
	v_add_f32_e32 v204, v128, v114
	v_add_f32_e32 v205, v128, v115
	v_add_f32_e32 v214, v178, v104
	v_add_f32_e32 v215, v178, v105
	v_add_f32_e32 v216, v178, v106
	v_add_f32_e32 v217, v178, v107
	v_add_f32_e32 v218, v178, v138
	v_add_f32_e32 v219, v178, v139
	v_add_f32_e32 v220, v178, v140
	v_add_f32_e32 v221, v178, v141
	v_exp_f32_e32 v198, v198
	v_exp_f32_e32 v199, v199
	v_exp_f32_e32 v200, v200
	v_exp_f32_e32 v201, v201
	v_exp_f32_e32 v202, v202
	v_exp_f32_e32 v203, v203
	v_exp_f32_e32 v204, v204
	v_exp_f32_e32 v205, v205
	v_exp_f32_e32 v214, v214
	v_exp_f32_e32 v215, v215
	v_exp_f32_e32 v216, v216
	v_exp_f32_e32 v217, v217
	v_exp_f32_e32 v218, v218
	v_exp_f32_e32 v219, v219
	v_exp_f32_e32 v220, v220
	v_exp_f32_e32 v221, v221
	v_add_f32_e32 v198, 1.0, v198
	v_add_f32_e32 v199, 1.0, v199
	v_add_f32_e32 v200, 1.0, v200
	v_add_f32_e32 v201, 1.0, v201
	v_add_f32_e32 v202, 1.0, v202
	v_add_f32_e32 v203, 1.0, v203
	v_add_f32_e32 v204, 1.0, v204
	v_add_f32_e32 v205, 1.0, v205
	v_add_f32_e32 v214, 1.0, v214
	v_add_f32_e32 v215, 1.0, v215
	v_add_f32_e32 v216, 1.0, v216
	v_add_f32_e32 v217, 1.0, v217
	v_add_f32_e32 v218, 1.0, v218
	v_add_f32_e32 v219, 1.0, v219
	v_add_f32_e32 v220, 1.0, v220
	v_add_f32_e32 v221, 1.0, v221
	v_rcp_f32_e32 v198, v198
	v_rcp_f32_e32 v199, v199
	v_rcp_f32_e32 v200, v200
	v_rcp_f32_e32 v201, v201
	v_rcp_f32_e32 v202, v202
	v_rcp_f32_e32 v203, v203
	v_rcp_f32_e32 v204, v204
	v_rcp_f32_e32 v205, v205
	v_add_f32_e32 v222, v133, v108
	v_add_f32_e32 v223, v133, v109
	v_add_f32_e32 v224, v133, v110
	v_add_f32_e32 v225, v133, v111
	v_add_f32_e32 v226, v133, v142
	v_add_f32_e32 v227, v133, v143
	v_add_f32_e32 v228, v133, v144
	v_add_f32_e32 v229, v133, v145
	v_mul_f32_e32 v198, v179, v198
	v_mul_f32_e32 v199, v179, v199
	v_mul_f32_e32 v200, v179, v200
	v_mul_f32_e32 v201, v179, v201
	v_mul_f32_e32 v202, v179, v202
	v_mul_f32_e32 v203, v179, v203
	v_mul_f32_e32 v204, v179, v204
	v_mul_f32_e32 v205, v179, v205
	v_exp_f32_e32 v120, v198
	v_exp_f32_e32 v121, v199
	v_exp_f32_e32 v122, v200
	v_exp_f32_e32 v123, v201
	v_exp_f32_e32 v124, v202
	v_exp_f32_e32 v125, v203
	v_exp_f32_e32 v126, v204
	v_exp_f32_e32 v127, v205
	s_nop 0
	v_fma_f32 v206, -v120, v120, 1.0
	v_fma_f32 v207, -v121, v121, 1.0
	v_fma_f32 v208, -v122, v122, 1.0
	v_fma_f32 v209, -v123, v123, 1.0
	v_fma_f32 v210, -v124, v124, 1.0
	v_fma_f32 v211, -v125, v125, 1.0
	v_fma_f32 v212, -v126, v126, 1.0
	v_fma_f32 v213, -v127, v127, 1.0
	v_max_f32_e32 v206, 0xda24260, v206
	v_max_f32_e32 v207, 0xda24260, v207
	v_max_f32_e32 v208, 0xda24260, v208
	v_max_f32_e32 v209, 0xda24260, v209
	v_max_f32_e32 v210, 0xda24260, v210
	v_max_f32_e32 v211, 0xda24260, v211
	v_max_f32_e32 v212, 0xda24260, v212
	v_max_f32_e32 v213, 0xda24260, v213
	v_mul_f32_e32 v198, v214, v206
	v_mul_f32_e32 v199, v215, v207
	v_mul_f32_e32 v200, v216, v208
	v_mul_f32_e32 v201, v217, v209
	v_mul_f32_e32 v202, v218, v210
	v_mul_f32_e32 v203, v219, v211
	v_mul_f32_e32 v204, v220, v212
	v_mul_f32_e32 v205, v221, v213
	v_mul_f32_e32 v214, v214, v198
	v_mul_f32_e32 v215, v215, v199
	v_mul_f32_e32 v216, v216, v200
	v_mul_f32_e32 v217, v217, v201
	v_mul_f32_e32 v218, v218, v202
	v_mul_f32_e32 v219, v219, v203
	v_mul_f32_e32 v220, v220, v204
	v_mul_f32_e32 v221, v221, v205
	v_rsq_f32_e32 v214, v214
	v_rsq_f32_e32 v215, v215
	v_rsq_f32_e32 v216, v216
	v_rsq_f32_e32 v217, v217
	v_rsq_f32_e32 v218, v218
	v_rsq_f32_e32 v219, v219
	v_rsq_f32_e32 v220, v220
	v_rsq_f32_e32 v221, v221
	v_mul_f32_e32 v222, v222, v206
	v_mul_f32_e32 v223, v223, v207
	v_mul_f32_e32 v224, v224, v208
	v_mul_f32_e32 v225, v225, v209
	v_mul_f32_e32 v226, v226, v210
	v_mul_f32_e32 v227, v227, v211
	v_mul_f32_e32 v228, v228, v212
	v_mul_f32_e32 v229, v229, v213
	s_nop 0
	v_mul_f32_e32 v170, v222, v214
	v_mul_f32_e32 v171, v223, v215
	v_mul_f32_e32 v172, v224, v216
	v_mul_f32_e32 v173, v225, v217
	v_mul_f32_e32 v174, v226, v218
	v_mul_f32_e32 v175, v227, v219
	v_mul_f32_e32 v176, v228, v220
	v_mul_f32_e32 v177, v229, v221
	v_mov_b32_e32 v198, v177
	v_mov_b32_e32 v199, v127
	v_fma_f32 v198, v126, v198, v176
	v_mul_f32_e32 v199, v199, v126
	v_fma_f32 v198, v125, v198, v175
	v_mul_f32_e32 v199, v199, v125
	v_fma_f32 v198, v124, v198, v174
	v_mul_f32_e32 v199, v199, v124
	v_fma_f32 v198, v123, v198, v173
	v_mul_f32_e32 v199, v199, v123
	v_fma_f32 v198, v122, v198, v172
	v_mul_f32_e32 v199, v199, v122
	v_fma_f32 v198, v121, v198, v171
	v_mul_f32_e32 v199, v199, v121
	v_fma_f32 v198, v120, v198, v170
	v_mul_f32_e32 v199, v199, v120
	ds_bpermute_b32 v164, v117, v199 offset:0
	ds_bpermute_b32 v246, v117, v198 offset:0
	ds_bpermute_b32 v165, v117, v199 offset:64
	ds_bpermute_b32 v247, v117, v198 offset:64
	ds_bpermute_b32 v166, v117, v199 offset:128
	ds_bpermute_b32 v248, v117, v198 offset:128
	ds_bpermute_b32 v167, v117, v199 offset:192
	ds_bpermute_b32 v249, v117, v198 offset:192
	s_waitcnt lgkmcnt(0)
	v_mov_b32_e32 v251, v249
	v_mov_b32_e32 v250, v167
	v_fma_f32 v251, v251, v166, v248
	v_mul_f32_e32 v250, v250, v166
	v_fma_f32 v251, v251, v165, v247
	v_mul_f32_e32 v250, v250, v165
	v_fma_f32 v251, v251, v164, v246
	v_mul_f32_e32 v250, v250, v164
	s_mov_b64 exec, s[10:11]
	ds_write_b64 v182, v[250:251] offset:0
	s_mov_b64 exec, -1
	s_waitcnt lgkmcnt(0)
	s_barrier
	ds_read2_b64 v[4:7], v183 offset0:0 offset1:16
	s_add_i32 s52, s4, 0
	s_sub_i32 s52, 31, s52
	s_lshl_b32 s52, s52, 12
	v_add_u32_e32 v197, s52, v116
	s_cmp_ge_u32 s4, 16
	s_cselect_b64 s[58:59], -1, 0
	ds_read_u16 v206, v197 offset:0
	ds_read_u16 v207, v197 offset:64
	ds_read_u16 v208, v197 offset:128
	ds_read_u16 v209, v197 offset:192
	ds_read_u16 v210, v197 offset:256
	ds_read_u16 v211, v197 offset:320
	ds_read_u16 v212, v197 offset:384
	ds_read_u16 v213, v197 offset:448
	s_waitcnt lgkmcnt(8)
	v_fma_f32 v198, v180, v6, v7
	v_cndmask_b32_e64 v199, v180, v198, s[24:25]
	v_fma_f32 v180, v198, v4, v5
	v_fma_f32 v200, v199, v167, v249
	v_cndmask_b32_e64 v199, v199, v200, s[16:17]
	v_fma_f32 v200, v199, v166, v248
	v_cndmask_b32_e64 v199, v199, v200, s[20:21]
	v_fma_f32 v200, v199, v165, v247
	v_cndmask_b32_e64 v199, v199, v200, s[22:23]
	v_fma_f32 v221, v127, v199, v177
	v_fma_f32 v220, v126, v221, v176
	v_fma_f32 v219, v125, v220, v175
	v_fma_f32 v218, v124, v219, v174
	v_fma_f32 v217, v123, v218, v173
	v_fma_f32 v216, v122, v217, v172
	v_fma_f32 v215, v121, v216, v171
	v_fma_f32 v214, v120, v215, v170
	s_waitcnt lgkmcnt(0)
	v_lshlrev_b32_e32 v206, 16, v206
	v_lshlrev_b32_e32 v207, 16, v207
	v_lshlrev_b32_e32 v208, 16, v208
	v_lshlrev_b32_e32 v209, 16, v209
	v_lshlrev_b32_e32 v210, 16, v210
	v_lshlrev_b32_e32 v211, 16, v211
	v_lshlrev_b32_e32 v212, 16, v212
	v_lshlrev_b32_e32 v213, 16, v213
	v_cndmask_b32_e64 v206, 0, v206, s[58:59]
	v_cndmask_b32_e64 v207, 0, v207, s[58:59]
	v_cndmask_b32_e64 v208, 0, v208, s[58:59]
	v_cndmask_b32_e64 v209, 0, v209, s[58:59]
	v_cndmask_b32_e64 v210, 0, v210, s[58:59]
	v_cndmask_b32_e64 v211, 0, v211, s[58:59]
	v_cndmask_b32_e64 v212, 0, v212, s[58:59]
	v_cndmask_b32_e64 v213, 0, v213, s[58:59]
	v_add_f32_e32 v214, v214, v206
	v_add_f32_e32 v215, v215, v207
	v_add_f32_e32 v216, v216, v208
	v_add_f32_e32 v217, v217, v209
	v_add_f32_e32 v218, v218, v210
	v_add_f32_e32 v219, v219, v211
	v_add_f32_e32 v220, v220, v212
	v_add_f32_e32 v221, v221, v213
	v_cvt_pk_bf16_f32 v206, v214, v215
	v_cvt_pk_bf16_f32 v208, v216, v217
	v_cvt_pk_bf16_f32 v210, v218, v219
	v_cvt_pk_bf16_f32 v212, v220, v221
	ds_write_b16 v197, v206 offset:0
	ds_write_b16_d16_hi v197, v206 offset:64
	ds_write_b16 v197, v208 offset:128
	ds_write_b16_d16_hi v197, v208 offset:192
	ds_write_b16 v197, v210 offset:256
	ds_write_b16_d16_hi v197, v210 offset:320
	ds_write_b16 v197, v212 offset:384
	ds_write_b16_d16_hi v197, v212 offset:448
	ds_read_b128 v[198:201], v130 offset:0
	ds_read_b128 v[202:205], v131 offset:0
	ds_read_b128 v[206:209], v130 offset:144
	ds_read_b128 v[210:213], v131 offset:144
	ds_read_b128 v[214:217], v130 offset:288
	ds_read_b128 v[218:221], v131 offset:288
	ds_read_b128 v[222:225], v130 offset:432
	ds_read_b128 v[226:229], v131 offset:432
	s_waitcnt lgkmcnt(7)
	v_mfma_f32_16x16x32_bf16 v[100:103], v[198:201], v[20:23], 0
	v_mfma_f32_16x16x32_bf16 v[104:107], v[198:201], v[52:55], 0
	v_mfma_f32_16x16x32_bf16 v[108:111], v[198:201], v[84:87], 0
	s_waitcnt lgkmcnt(6)
	v_mfma_f32_16x16x32_bf16 v[100:103], v[202:205], v[24:27], v[100:103]
	v_mfma_f32_16x16x32_bf16 v[104:107], v[202:205], v[56:59], v[104:107]
	ds_read_b128 v[198:201], v130 offset:576
	ds_read_b128 v[202:205], v131 offset:576
	s_waitcnt lgkmcnt(7)
	v_mfma_f32_16x16x32_bf16 v[100:103], v[206:209], v[28:31], v[100:103]
	v_mfma_f32_16x16x32_bf16 v[104:107], v[206:209], v[60:63], v[104:107]
	v_mfma_f32_16x16x32_bf16 v[108:111], v[206:209], v[88:91], v[108:111]
	s_waitcnt lgkmcnt(6)
	v_mfma_f32_16x16x32_bf16 v[100:103], v[210:213], v[32:35], v[100:103]
	v_mfma_f32_16x16x32_bf16 v[104:107], v[210:213], v[64:67], v[104:107]
	ds_read_b128 v[206:209], v130 offset:720
	ds_read_b128 v[210:213], v131 offset:720
	s_waitcnt lgkmcnt(7)
	v_mfma_f32_16x16x32_bf16 v[100:103], v[214:217], v[36:39], v[100:103]
	v_mfma_f32_16x16x32_bf16 v[104:107], v[214:217], v[68:71], v[104:107]
	v_mfma_f32_16x16x32_bf16 v[108:111], v[214:217], v[92:95], v[108:111]
	s_waitcnt lgkmcnt(6)
	v_mfma_f32_16x16x32_bf16 v[100:103], v[218:221], v[40:43], v[100:103]
	v_mfma_f32_16x16x32_bf16 v[104:107], v[218:221], v[72:75], v[104:107]
	ds_read_b128 v[214:217], v130 offset:864
	ds_read_b128 v[218:221], v131 offset:864
	s_waitcnt lgkmcnt(7)
	v_mfma_f32_16x16x32_bf16 v[100:103], v[222:225], v[44:47], v[100:103]
	v_mfma_f32_16x16x32_bf16 v[104:107], v[222:225], v[76:79], v[104:107]
	v_mfma_f32_16x16x32_bf16 v[108:111], v[222:225], v[96:99], v[108:111]
	s_waitcnt lgkmcnt(6)
	v_mfma_f32_16x16x32_bf16 v[100:103], v[226:229], v[48:51], v[100:103]
	v_mfma_f32_16x16x32_bf16 v[104:107], v[226:229], v[80:83], v[104:107]
	ds_read_b128 v[222:225], v130 offset:1008
	ds_read_b128 v[226:229], v131 offset:1008
	s_waitcnt lgkmcnt(7)
	v_mfma_f32_16x16x32_bf16 v[112:115], v[198:201], v[20:23], 0
	v_mfma_f32_16x16x32_bf16 v[138:141], v[198:201], v[52:55], 0
	v_mfma_f32_16x16x32_bf16 v[142:145], v[198:201], v[84:87], 0
	s_waitcnt lgkmcnt(6)
	v_mfma_f32_16x16x32_bf16 v[112:115], v[202:205], v[24:27], v[112:115]
	v_mfma_f32_16x16x32_bf16 v[138:141], v[202:205], v[56:59], v[138:141]
	s_waitcnt lgkmcnt(5)
	v_mfma_f32_16x16x32_bf16 v[112:115], v[206:209], v[28:31], v[112:115]
	v_mfma_f32_16x16x32_bf16 v[138:141], v[206:209], v[60:63], v[138:141]
	v_mfma_f32_16x16x32_bf16 v[142:145], v[206:209], v[88:91], v[142:145]
	s_waitcnt lgkmcnt(4)
	v_mfma_f32_16x16x32_bf16 v[112:115], v[210:213], v[32:35], v[112:115]
	v_mfma_f32_16x16x32_bf16 v[138:141], v[210:213], v[64:67], v[138:141]
	s_waitcnt lgkmcnt(3)
	v_mfma_f32_16x16x32_bf16 v[112:115], v[214:217], v[36:39], v[112:115]
	v_mfma_f32_16x16x32_bf16 v[138:141], v[214:217], v[68:71], v[138:141]
	v_mfma_f32_16x16x32_bf16 v[142:145], v[214:217], v[92:95], v[142:145]
	s_waitcnt lgkmcnt(2)
	v_mfma_f32_16x16x32_bf16 v[112:115], v[218:221], v[40:43], v[112:115]
	v_mfma_f32_16x16x32_bf16 v[138:141], v[218:221], v[72:75], v[138:141]
	s_waitcnt lgkmcnt(1)
	v_mfma_f32_16x16x32_bf16 v[112:115], v[222:225], v[44:47], v[112:115]
	v_mfma_f32_16x16x32_bf16 v[138:141], v[222:225], v[76:79], v[138:141]
	v_mfma_f32_16x16x32_bf16 v[142:145], v[222:225], v[96:99], v[142:145]
	s_waitcnt lgkmcnt(0)
	v_mfma_f32_16x16x32_bf16 v[112:115], v[226:229], v[48:51], v[112:115]
	v_mfma_f32_16x16x32_bf16 v[138:141], v[226:229], v[80:83], v[138:141]
	s_waitcnt lgkmcnt(0)
	s_barrier
	s_waitcnt vmcnt(3)
	ds_write_b128 v134, v[230:233]
	ds_write_b128 v134, v[234:237] offset:4608
	ds_write_b128 v135, v[238:241]
	s_add_i32 s52, s4, 4
	s_min_u32 s52, s52, 31
	s_sub_i32 s52, 31, s52
	s_lshl_b32 s52, s52, 13
	s_add_u32 s26, s50, s52
	s_addc_u32 s27, s51, 0
	global_load_dwordx4 v[230:233], v154, s[26:27]
	global_load_dwordx4 v[234:237], v155, s[26:27]
	global_load_dwordx4 v[238:241], v159, s[26:27]
	v_add_f32_e32 v198, v128, v100
	v_add_f32_e32 v199, v128, v101
	v_add_f32_e32 v200, v128, v102
	v_add_f32_e32 v201, v128, v103
	v_add_f32_e32 v202, v128, v112
	v_add_f32_e32 v203, v128, v113
	v_add_f32_e32 v204, v128, v114
	v_add_f32_e32 v205, v128, v115
	v_add_f32_e32 v214, v178, v104
	v_add_f32_e32 v215, v178, v105
	v_add_f32_e32 v216, v178, v106
	v_add_f32_e32 v217, v178, v107
	v_add_f32_e32 v218, v178, v138
	v_add_f32_e32 v219, v178, v139
	v_add_f32_e32 v220, v178, v140
	v_add_f32_e32 v221, v178, v141
	v_exp_f32_e32 v198, v198
	v_exp_f32_e32 v199, v199
	v_exp_f32_e32 v200, v200
	v_exp_f32_e32 v201, v201
	v_exp_f32_e32 v202, v202
	v_exp_f32_e32 v203, v203
	v_exp_f32_e32 v204, v204
	v_exp_f32_e32 v205, v205
	v_exp_f32_e32 v214, v214
	v_exp_f32_e32 v215, v215
	v_exp_f32_e32 v216, v216
	v_exp_f32_e32 v217, v217
	v_exp_f32_e32 v218, v218
	v_exp_f32_e32 v219, v219
	v_exp_f32_e32 v220, v220
	v_exp_f32_e32 v221, v221
	v_add_f32_e32 v198, 1.0, v198
	v_add_f32_e32 v199, 1.0, v199
	v_add_f32_e32 v200, 1.0, v200
	v_add_f32_e32 v201, 1.0, v201
	v_add_f32_e32 v202, 1.0, v202
	v_add_f32_e32 v203, 1.0, v203
	v_add_f32_e32 v204, 1.0, v204
	v_add_f32_e32 v205, 1.0, v205
	v_add_f32_e32 v214, 1.0, v214
	v_add_f32_e32 v215, 1.0, v215
	v_add_f32_e32 v216, 1.0, v216
	v_add_f32_e32 v217, 1.0, v217
	v_add_f32_e32 v218, 1.0, v218
	v_add_f32_e32 v219, 1.0, v219
	v_add_f32_e32 v220, 1.0, v220
	v_add_f32_e32 v221, 1.0, v221
	v_rcp_f32_e32 v198, v198
	v_rcp_f32_e32 v199, v199
	v_rcp_f32_e32 v200, v200
	v_rcp_f32_e32 v201, v201
	v_rcp_f32_e32 v202, v202
	v_rcp_f32_e32 v203, v203
	v_rcp_f32_e32 v204, v204
	v_rcp_f32_e32 v205, v205
	v_add_f32_e32 v222, v133, v108
	v_add_f32_e32 v223, v133, v109
	v_add_f32_e32 v224, v133, v110
	v_add_f32_e32 v225, v133, v111
	v_add_f32_e32 v226, v133, v142
	v_add_f32_e32 v227, v133, v143
	v_add_f32_e32 v228, v133, v144
	v_add_f32_e32 v229, v133, v145
	v_mul_f32_e32 v198, v179, v198
	v_mul_f32_e32 v199, v179, v199
	v_mul_f32_e32 v200, v179, v200
	v_mul_f32_e32 v201, v179, v201
	v_mul_f32_e32 v202, v179, v202
	v_mul_f32_e32 v203, v179, v203
	v_mul_f32_e32 v204, v179, v204
	v_mul_f32_e32 v205, v179, v205
	v_exp_f32_e32 v120, v198
	v_exp_f32_e32 v121, v199
	v_exp_f32_e32 v122, v200
	v_exp_f32_e32 v123, v201
	v_exp_f32_e32 v124, v202
	v_exp_f32_e32 v125, v203
	v_exp_f32_e32 v126, v204
	v_exp_f32_e32 v127, v205
	s_nop 0
	v_fma_f32 v206, -v120, v120, 1.0
	v_fma_f32 v207, -v121, v121, 1.0
	v_fma_f32 v208, -v122, v122, 1.0
	v_fma_f32 v209, -v123, v123, 1.0
	v_fma_f32 v210, -v124, v124, 1.0
	v_fma_f32 v211, -v125, v125, 1.0
	v_fma_f32 v212, -v126, v126, 1.0
	v_fma_f32 v213, -v127, v127, 1.0
	v_max_f32_e32 v206, 0xda24260, v206
	v_max_f32_e32 v207, 0xda24260, v207
	v_max_f32_e32 v208, 0xda24260, v208
	v_max_f32_e32 v209, 0xda24260, v209
	v_max_f32_e32 v210, 0xda24260, v210
	v_max_f32_e32 v211, 0xda24260, v211
	v_max_f32_e32 v212, 0xda24260, v212
	v_max_f32_e32 v213, 0xda24260, v213
	v_mul_f32_e32 v198, v214, v206
	v_mul_f32_e32 v199, v215, v207
	v_mul_f32_e32 v200, v216, v208
	v_mul_f32_e32 v201, v217, v209
	v_mul_f32_e32 v202, v218, v210
	v_mul_f32_e32 v203, v219, v211
	v_mul_f32_e32 v204, v220, v212
	v_mul_f32_e32 v205, v221, v213
	v_mul_f32_e32 v214, v214, v198
	v_mul_f32_e32 v215, v215, v199
	v_mul_f32_e32 v216, v216, v200
	v_mul_f32_e32 v217, v217, v201
	v_mul_f32_e32 v218, v218, v202
	v_mul_f32_e32 v219, v219, v203
	v_mul_f32_e32 v220, v220, v204
	v_mul_f32_e32 v221, v221, v205
	v_rsq_f32_e32 v214, v214
	v_rsq_f32_e32 v215, v215
	v_rsq_f32_e32 v216, v216
	v_rsq_f32_e32 v217, v217
	v_rsq_f32_e32 v218, v218
	v_rsq_f32_e32 v219, v219
	v_rsq_f32_e32 v220, v220
	v_rsq_f32_e32 v221, v221
	v_mul_f32_e32 v222, v222, v206
	v_mul_f32_e32 v223, v223, v207
	v_mul_f32_e32 v224, v224, v208
	v_mul_f32_e32 v225, v225, v209
	v_mul_f32_e32 v226, v226, v210
	v_mul_f32_e32 v227, v227, v211
	v_mul_f32_e32 v228, v228, v212
	v_mul_f32_e32 v229, v229, v213
	s_nop 0
	v_mul_f32_e32 v170, v222, v214
	v_mul_f32_e32 v171, v223, v215
	v_mul_f32_e32 v172, v224, v216
	v_mul_f32_e32 v173, v225, v217
	v_mul_f32_e32 v174, v226, v218
	v_mul_f32_e32 v175, v227, v219
	v_mul_f32_e32 v176, v228, v220
	v_mul_f32_e32 v177, v229, v221
	v_mov_b32_e32 v198, v177
	v_mov_b32_e32 v199, v127
	v_fma_f32 v198, v126, v198, v176
	v_mul_f32_e32 v199, v199, v126
	v_fma_f32 v198, v125, v198, v175
	v_mul_f32_e32 v199, v199, v125
	v_fma_f32 v198, v124, v198, v174
	v_mul_f32_e32 v199, v199, v124
	v_fma_f32 v198, v123, v198, v173
	v_mul_f32_e32 v199, v199, v123
	v_fma_f32 v198, v122, v198, v172
	v_mul_f32_e32 v199, v199, v122
	v_fma_f32 v198, v121, v198, v171
	v_mul_f32_e32 v199, v199, v121
	v_fma_f32 v198, v120, v198, v170
	v_mul_f32_e32 v199, v199, v120
	ds_bpermute_b32 v164, v117, v199 offset:0
	ds_bpermute_b32 v246, v117, v198 offset:0
	ds_bpermute_b32 v165, v117, v199 offset:64
	ds_bpermute_b32 v247, v117, v198 offset:64
	ds_bpermute_b32 v166, v117, v199 offset:128
	ds_bpermute_b32 v248, v117, v198 offset:128
	ds_bpermute_b32 v167, v117, v199 offset:192
	ds_bpermute_b32 v249, v117, v198 offset:192
	s_waitcnt lgkmcnt(0)
	v_mov_b32_e32 v251, v249
	v_mov_b32_e32 v250, v167
	v_fma_f32 v251, v251, v166, v248
	v_mul_f32_e32 v250, v250, v166
	v_fma_f32 v251, v251, v165, v247
	v_mul_f32_e32 v250, v250, v165
	v_fma_f32 v251, v251, v164, v246
	v_mul_f32_e32 v250, v250, v164
	s_mov_b64 exec, s[10:11]
	ds_write_b64 v182, v[250:251] offset:1024
	s_mov_b64 exec, -1
	s_waitcnt lgkmcnt(0)
	s_barrier
	ds_read2_b64 v[4:7], v183 offset0:128 offset1:144
	s_add_i32 s52, s4, 1
	s_sub_i32 s52, 31, s52
	s_lshl_b32 s52, s52, 12
	v_add_u32_e32 v197, s52, v116
	s_cmp_ge_u32 s4, 16
	s_cselect_b64 s[58:59], -1, 0
	ds_read_u16 v206, v197 offset:0
	ds_read_u16 v207, v197 offset:64
	ds_read_u16 v208, v197 offset:128
	ds_read_u16 v209, v197 offset:192
	ds_read_u16 v210, v197 offset:256
	ds_read_u16 v211, v197 offset:320
	ds_read_u16 v212, v197 offset:384
	ds_read_u16 v213, v197 offset:448
	s_waitcnt lgkmcnt(8)
	v_fma_f32 v198, v180, v6, v7
	v_cndmask_b32_e64 v199, v180, v198, s[24:25]
	v_fma_f32 v180, v198, v4, v5
	v_fma_f32 v200, v199, v167, v249
	v_cndmask_b32_e64 v199, v199, v200, s[16:17]
	v_fma_f32 v200, v199, v166, v248
	v_cndmask_b32_e64 v199, v199, v200, s[20:21]
	v_fma_f32 v200, v199, v165, v247
	v_cndmask_b32_e64 v199, v199, v200, s[22:23]
	v_fma_f32 v221, v127, v199, v177
	v_fma_f32 v220, v126, v221, v176
	v_fma_f32 v219, v125, v220, v175
	v_fma_f32 v218, v124, v219, v174
	v_fma_f32 v217, v123, v218, v173
	v_fma_f32 v216, v122, v217, v172
	v_fma_f32 v215, v121, v216, v171
	v_fma_f32 v214, v120, v215, v170
	s_waitcnt lgkmcnt(0)
	v_lshlrev_b32_e32 v206, 16, v206
	v_lshlrev_b32_e32 v207, 16, v207
	v_lshlrev_b32_e32 v208, 16, v208
	v_lshlrev_b32_e32 v209, 16, v209
	v_lshlrev_b32_e32 v210, 16, v210
	v_lshlrev_b32_e32 v211, 16, v211
	v_lshlrev_b32_e32 v212, 16, v212
	v_lshlrev_b32_e32 v213, 16, v213
	v_cndmask_b32_e64 v206, 0, v206, s[58:59]
	v_cndmask_b32_e64 v207, 0, v207, s[58:59]
	v_cndmask_b32_e64 v208, 0, v208, s[58:59]
	v_cndmask_b32_e64 v209, 0, v209, s[58:59]
	v_cndmask_b32_e64 v210, 0, v210, s[58:59]
	v_cndmask_b32_e64 v211, 0, v211, s[58:59]
	v_cndmask_b32_e64 v212, 0, v212, s[58:59]
	v_cndmask_b32_e64 v213, 0, v213, s[58:59]
	v_add_f32_e32 v214, v214, v206
	v_add_f32_e32 v215, v215, v207
	v_add_f32_e32 v216, v216, v208
	v_add_f32_e32 v217, v217, v209
	v_add_f32_e32 v218, v218, v210
	v_add_f32_e32 v219, v219, v211
	v_add_f32_e32 v220, v220, v212
	v_add_f32_e32 v221, v221, v213
	v_cvt_pk_bf16_f32 v206, v214, v215
	v_cvt_pk_bf16_f32 v208, v216, v217
	v_cvt_pk_bf16_f32 v210, v218, v219
	v_cvt_pk_bf16_f32 v212, v220, v221
	ds_write_b16 v197, v206 offset:0
	ds_write_b16_d16_hi v197, v206 offset:64
	ds_write_b16 v197, v208 offset:128
	ds_write_b16_d16_hi v197, v208 offset:192
	ds_write_b16 v197, v210 offset:256
	ds_write_b16_d16_hi v197, v210 offset:320
	ds_write_b16 v197, v212 offset:384
	ds_write_b16_d16_hi v197, v212 offset:448
	s_add_i32 s4, s4, 2
	s_cmp_lt_u32 s4, 32
	s_cbranch_scc1 .Lrec2_loop_d1
.Lrec2_done:
.LBB0_679:
	s_mul_hi_i32 s4, s69, 0x600000
	s_mul_i32 s69, s69, 0x600000
	s_add_u32 s26, s30, s69
	s_addc_u32 s4, s31, s4
	s_lshl_b32 s27, s68, 1
	s_add_u32 s26, s26, s27
	s_addc_u32 s4, s4, 0
	s_lshl_b32 s27, s67, 1
	s_waitcnt lgkmcnt(0)
	s_barrier
	s_add_u32 s26, s26, s27
	s_addc_u32 s27, s4, 0
	s_waitcnt vmcnt(0)
	v_mov_b32_e32 v133, v129
	v_lshl_add_u64 v[4:5], s[26:27], 0, v[132:133]
	s_mov_b32 s4, 0
	v_mov_b32_e32 v6, v181

	.amdhsa_kernel _Z8mega_fwd4Ptrs
		.amdhsa_group_segment_fixed_size 256
		.amdhsa_private_segment_fixed_size 0
		.amdhsa_kernarg_size 424
		.amdhsa_user_sgpr_count 2
		.amdhsa_user_sgpr_dispatch_ptr 0
		.amdhsa_user_sgpr_queue_ptr 0
		.amdhsa_user_sgpr_kernarg_segment_ptr 1
		.amdhsa_user_sgpr_dispatch_id 0
		.amdhsa_user_sgpr_kernarg_preload_length 0
		.amdhsa_user_sgpr_kernarg_preload_offset 0
		.amdhsa_user_sgpr_private_segment_size 0
		.amdhsa_uses_dynamic_stack 0
		.amdhsa_enable_private_segment 0
		.amdhsa_system_sgpr_workgroup_id_x 1
		.amdhsa_system_sgpr_workgroup_id_y 0
		.amdhsa_system_sgpr_workgroup_id_z 0
		.amdhsa_system_sgpr_workgroup_info 0
		.amdhsa_system_vgpr_workitem_id 2
		.amdhsa_next_free_vgpr 256
		.amdhsa_next_free_sgpr 102
		.amdhsa_accum_offset 256
		.amdhsa_reserve_vcc 1
		.amdhsa_float_round_mode_32 0
		.amdhsa_float_round_mode_16_64 0
		.amdhsa_float_denorm_mode_32 3
		.amdhsa_float_denorm_mode_16_64 3
		.amdhsa_dx10_clamp 1
		.amdhsa_ieee_mode 1
		.amdhsa_fp16_overflow 0
		.amdhsa_tg_split 0
		.amdhsa_exception_fp_ieee_invalid_op 0
		.amdhsa_exception_fp_denorm_src 0
		.amdhsa_exception_fp_ieee_div_zero 0
		.amdhsa_exception_fp_ieee_overflow 0
		.amdhsa_exception_fp_ieee_underflow 0
		.amdhsa_exception_fp_ieee_inexact 0
		.amdhsa_exception_int_div_zero 0
	.end_amdhsa_kernel

amdhsa.kernels:
  - .agpr_count:     0
    .args:
      - .offset:         0
        .size:           168
        .value_kind:     by_value
      - .offset:         168
        .size:           4
        .value_kind:     hidden_block_count_x
      - .offset:         172
        .size:           4
        .value_kind:     hidden_block_count_y
      - .offset:         176
        .size:           4
        .value_kind:     hidden_block_count_z
      - .offset:         180
        .size:           2
        .value_kind:     hidden_group_size_x
      - .offset:         182
        .size:           2
        .value_kind:     hidden_group_size_y
      - .offset:         184
        .size:           2
        .value_kind:     hidden_group_size_z
      - .offset:         186
        .size:           2
        .value_kind:     hidden_remainder_x
      - .offset:         188
        .size:           2
        .value_kind:     hidden_remainder_y
      - .offset:         190
        .size:           2
        .value_kind:     hidden_remainder_z
      - .offset:         208
        .size:           8
        .value_kind:     hidden_global_offset_x
      - .offset:         216
        .size:           8
        .value_kind:     hidden_global_offset_y
      - .offset:         224
        .size:           8
        .value_kind:     hidden_global_offset_z
      - .offset:         232
        .size:           2
        .value_kind:     hidden_grid_dims
      - .offset:         288
        .size:           4
        .value_kind:     hidden_dynamic_lds_size
    .group_segment_fixed_size: 256
    .kernarg_segment_align: 8
    .kernarg_segment_size: 424
    .language:       OpenCL C
    .language_version:
      - 2
      - 0
    .max_flat_workgroup_size: 512
    .name:           _Z8mega_fwd4Ptrs
    .private_segment_fixed_size: 0
    .sgpr_count:     108
    .sgpr_spill_count: 33
    .symbol:         _Z8mega_fwd4Ptrs.kd
    .uniform_work_group_size: 1
    .uses_dynamic_stack: false
    .vgpr_count:     256
    .vgpr_spill_count: 0
    .wavefront_size: 64
